# back-edge rotation (asm guide 7.11): K-loop counter/pointer/exit-test SALU moved ahead of the loop-back barrier in all four GEMM loops, on top of v34
# baseline (speedup 1.0000x reference)
; #define PG8_STAGE(bufoff, gbase, voff) do { _Pragma("unroll") for (int _i = 0; _i < 2; ++_i) \
;         __builtin_amdgcn_global_load_lds((const unsigned*)((const char*)(gbase) + (voff)[_i]), (LAS unsigned*)(lds + (bufoff) + ldsw + _i * 8192), 16, 0, 0); } while (0)
; #define PG8_LDA(dst, b, h) do { _Pragma("unroll") for (int m = 0; m < 4; ++m) _Pragma("unroll") for (int k = 0; k < 2; ++k) dst[m][k] = *(const LAS bf16x8*)(lds + PG8_SA(b, h) + aoff + m * 2048 + k * 1024); } while (0)
; #define PG8_LDB(dst, b, h) do { _Pragma("unroll") for (int n = 0; n < 2; ++n) _Pragma("unroll") for (int k = 0; k < 2; ++k) dst[n][k] = *(const LAS bf16x8*)(lds + PG8_SB(b, h) + boff + n * 2048 + k * 1024); } while (0)
; #define PG8_MMA(ai, bj, At, Bt) do { __builtin_amdgcn_s_setprio(1); _Pragma("unroll") for (int m = 0; m < 4; ++m) _Pragma("unroll") for (int n = 0; n < 2; ++n) _Pragma("unroll") for (int k = 0; k < 2; ++k) \
;         acc[ai][bj][m][n] = __builtin_amdgcn_mfma_f32_16x16x32_bf16(Bt[n][k], At[m][k], acc[ai][bj][m][n], 0, 0, 0); __builtin_amdgcn_s_setprio(0); } while (0)
; #define PG8_WAIT_V(n) asm volatile("s_waitcnt vmcnt(" #n ")" ::: "memory")
; #define PG8_WAIT_L(n) asm volatile("s_waitcnt lgkmcnt(" #n ")" ::: "memory")
; #define PG8_BAR __builtin_amdgcn_s_barrier()
; #define PG8_SCHED __builtin_amdgcn_sched_barrier(0)
; template <class Epi, bool ALIGN_EPI, bool SP2>
; __device__ __forceinline__ void gemm_phase(LAS unsigned char* lds, const Sched2& S, const Epi& E) {
;     ...
;         for (int t = 0; t < nt; t += 2) {
;             const bool last = (t == nt - 2);
;             const char* a1 = cA + (size_t)(t + 1) * kstep;
;             const char* a2 = last ? nA : cA + (size_t)(t + 2) * kstep; const char* b2 = last ? nB : cB + (size_t)(t + 2) * kstep;
;             const char* a3 = a2 + kstep; const char* b3 = b2 + kstep;
;             if constexpr (SP2) {
;             PG8_LDB(B0, 0, 0); PG8_LDB(B1, 0, 1); PG8_SCHED; PG8_LDA(At, 0, 0); PG8_STAGE(PG8_SA(1, 1), a1 + hstep, voffA);
;             PG8_WAIT_V(8); PG8_WAIT_L(0); PG8_BAR; PG8_MMA(0, 0, At, B0); PG8_MMA(0, 1, At, B1); PG8_BAR; PG8_SCHED;
;             PG8_LDA(At, 0, 1); PG8_STAGE(PG8_SB(0, 0), b2, voffB); PG8_STAGE(PG8_SB(0, 1), b2 + hstep, voffB); PG8_STAGE(PG8_SA(0, 0), a2, voffA);
;             PG8_WAIT_V(8); PG8_WAIT_L(0); PG8_BAR; PG8_MMA(1, 0, At, B0); PG8_MMA(1, 1, At, B1); PG8_BAR; PG8_SCHED;
.LBB0_190:
	ds_read_b128 v[144:147], v158
	ds_read_b128 v[148:151], v158 offset:1024
	ds_read_b128 v[162:165], v158 offset:2048
	ds_read_b128 v[166:169], v158 offset:3072
	ds_read_b128 v[170:173], v159
	ds_read_b128 v[174:177], v159 offset:1024
	ds_read_b128 v[178:181], v159 offset:2048
	ds_read_b128 v[182:185], v159 offset:3072
	s_add_u32 s58, s72, 0xfffc0080
	s_addc_u32 s59, s73, -1
	s_cmp_eq_u32 s43, 12
	s_cselect_b32 s77, s65, s59
	s_cselect_b32 s76, s64, s58
	s_cselect_b32 s75, s69, s41
	s_cselect_b32 s74, s68, s1
	v_lshl_add_u64 v[152:153], s[72:73], 0, v[140:141]
	s_add_i32 m0, s67, 0xc000
	ds_read_b128 v[186:189], v160
	ds_read_b128 v[190:193], v160 offset:1024
	ds_read_b128 v[194:197], v160 offset:2048
	ds_read_b128 v[198:201], v160 offset:3072
	ds_read_b128 v[202:205], v160 offset:4096
	ds_read_b128 v[206:209], v160 offset:5120
	ds_read_b128 v[210:213], v160 offset:6144
	ds_read_b128 v[214:217], v160 offset:7168
	global_load_lds_dwordx4 v[152:153], off
	v_lshl_add_u64 v[152:153], s[72:73], 0, v[142:143]
	s_add_i32 m0, s67, 0xe000
	s_nop 0
	global_load_lds_dwordx4 v[152:153], off
	s_waitcnt vmcnt(8)
	s_waitcnt lgkmcnt(0)
	s_barrier
	s_setprio 1
	s_waitcnt lgkmcnt(0)
	v_mfma_f32_16x16x32_bf16 v[126:129], v[144:147], v[186:189], v[126:129]
	v_mfma_f32_16x16x32_bf16 v[122:125], v[162:165], v[186:189], v[122:125]
	v_mfma_f32_16x16x32_bf16 v[110:113], v[144:147], v[194:197], v[110:113]
	v_mfma_f32_16x16x32_bf16 v[106:109], v[162:165], v[194:197], v[106:109]
	v_mfma_f32_16x16x32_bf16 v[94:97], v[144:147], v[202:205], v[94:97]
	v_mfma_f32_16x16x32_bf16 v[90:93], v[162:165], v[202:205], v[90:93]
	v_mfma_f32_16x16x32_bf16 v[78:81], v[144:147], v[210:213], v[78:81]
	v_mfma_f32_16x16x32_bf16 v[74:77], v[162:165], v[210:213], v[74:77]
	v_mfma_f32_16x16x32_bf16 v[126:129], v[148:151], v[190:193], v[126:129]
	v_mfma_f32_16x16x32_bf16 v[122:125], v[166:169], v[190:193], v[122:125]
	v_mfma_f32_16x16x32_bf16 v[110:113], v[148:151], v[198:201], v[110:113]
	v_mfma_f32_16x16x32_bf16 v[106:109], v[166:169], v[198:201], v[106:109]
	v_mfma_f32_16x16x32_bf16 v[94:97], v[148:151], v[206:209], v[94:97]
	v_mfma_f32_16x16x32_bf16 v[90:93], v[166:169], v[206:209], v[90:93]
	v_mfma_f32_16x16x32_bf16 v[78:81], v[148:151], v[214:217], v[78:81]
	v_mfma_f32_16x16x32_bf16 v[74:77], v[166:169], v[214:217], v[74:77]
	s_setprio 0
	s_setprio 1
	v_mfma_f32_16x16x32_bf16 v[118:121], v[170:173], v[186:189], v[118:121]
	v_mfma_f32_16x16x32_bf16 v[114:117], v[178:181], v[186:189], v[114:117]
	v_mfma_f32_16x16x32_bf16 v[102:105], v[170:173], v[194:197], v[102:105]
	v_mfma_f32_16x16x32_bf16 v[98:101], v[178:181], v[194:197], v[98:101]
	v_mfma_f32_16x16x32_bf16 v[86:89], v[170:173], v[202:205], v[86:89]
	v_mfma_f32_16x16x32_bf16 v[82:85], v[178:181], v[202:205], v[82:85]
	v_mfma_f32_16x16x32_bf16 v[70:73], v[170:173], v[210:213], v[70:73]
	v_mfma_f32_16x16x32_bf16 v[66:69], v[178:181], v[210:213], v[66:69]
	v_mfma_f32_16x16x32_bf16 v[118:121], v[174:177], v[190:193], v[118:121]
	v_mfma_f32_16x16x32_bf16 v[114:117], v[182:185], v[190:193], v[114:117]
	v_mfma_f32_16x16x32_bf16 v[102:105], v[174:177], v[198:201], v[102:105]
	v_mfma_f32_16x16x32_bf16 v[98:101], v[182:185], v[198:201], v[98:101]
	v_mfma_f32_16x16x32_bf16 v[86:89], v[174:177], v[206:209], v[86:89]
	v_mfma_f32_16x16x32_bf16 v[82:85], v[182:185], v[206:209], v[82:85]
	v_mfma_f32_16x16x32_bf16 v[70:73], v[174:177], v[214:217], v[70:73]
	v_mfma_f32_16x16x32_bf16 v[66:69], v[182:185], v[214:217], v[66:69]
	s_setprio 0
	s_barrier
	s_add_i32 s58, s88, s35
	v_lshl_add_u64 v[152:153], s[74:75], 0, v[132:133]
	s_mov_b32 m0, s58
	ds_read_b128 v[186:189], v160 offset:16384
	ds_read_b128 v[190:193], v160 offset:17408
	ds_read_b128 v[194:197], v160 offset:18432
	ds_read_b128 v[198:201], v160 offset:19456
	ds_read_b128 v[202:205], v160 offset:20480
	ds_read_b128 v[206:209], v160 offset:21504
	ds_read_b128 v[210:213], v160 offset:22528
	ds_read_b128 v[214:217], v160 offset:23552
	global_load_lds_dwordx4 v[152:153], off
	s_add_i32 m0, s58, 0x2000
	s_add_u32 s58, s74, 0x40000
	v_lshl_add_u64 v[218:219], s[74:75], 0, v[136:137]
	s_addc_u32 s59, s75, 0
	s_add_i32 s71, s89, s35
	global_load_lds_dwordx4 v[218:219], off
	v_lshl_add_u64 v[220:221], s[58:59], 0, v[132:133]
	s_mov_b32 m0, s71
	v_lshl_add_u64 v[222:223], s[76:77], 0, v[134:135]
	global_load_lds_dwordx4 v[220:221], off
	v_lshl_add_u64 v[220:221], s[58:59], 0, v[136:137]
	s_add_i32 m0, s71, 0x2000
	s_nop 0
	global_load_lds_dwordx4 v[220:221], off
	v_lshl_add_u64 v[220:221], s[76:77], 0, v[130:131]
	s_mov_b32 m0, s67
	s_nop 0
	global_load_lds_dwordx4 v[220:221], off
	s_mov_b32 m0, s80
	s_nop 0
	global_load_lds_dwordx4 v[222:223], off
	s_waitcnt vmcnt(8)
	s_waitcnt lgkmcnt(0)
	s_barrier
; #define PG8_STAGE(bufoff, gbase, voff) do { _Pragma("unroll") for (int _i = 0; _i < 2; ++_i) \
;         __builtin_amdgcn_global_load_lds((const unsigned*)((const char*)(gbase) + (voff)[_i]), (LAS unsigned*)(lds + (bufoff) + ldsw + _i * 8192), 16, 0, 0); } while (0)
; #define PG8_LDA(dst, b, h) do { _Pragma("unroll") for (int m = 0; m < 4; ++m) _Pragma("unroll") for (int k = 0; k < 2; ++k) dst[m][k] = *(const LAS bf16x8*)(lds + PG8_SA(b, h) + aoff + m * 2048 + k * 1024); } while (0)
; #define PG8_LDB(dst, b, h) do { _Pragma("unroll") for (int n = 0; n < 2; ++n) _Pragma("unroll") for (int k = 0; k < 2; ++k) dst[n][k] = *(const LAS bf16x8*)(lds + PG8_SB(b, h) + boff + n * 2048 + k * 1024); } while (0)
; #define PG8_MMA(ai, bj, At, Bt) do { __builtin_amdgcn_s_setprio(1); _Pragma("unroll") for (int m = 0; m < 4; ++m) _Pragma("unroll") for (int n = 0; n < 2; ++n) _Pragma("unroll") for (int k = 0; k < 2; ++k) \
;         acc[ai][bj][m][n] = __builtin_amdgcn_mfma_f32_16x16x32_bf16(Bt[n][k], At[m][k], acc[ai][bj][m][n], 0, 0, 0); __builtin_amdgcn_s_setprio(0); } while (0)
; #define PG8_WAIT_V(n) asm volatile("s_waitcnt vmcnt(" #n ")" ::: "memory")
; #define PG8_WAIT_L(n) asm volatile("s_waitcnt lgkmcnt(" #n ")" ::: "memory")
; #define PG8_BAR __builtin_amdgcn_s_barrier()
; #define PG8_SCHED __builtin_amdgcn_sched_barrier(0)
; template <class Epi, bool ALIGN_EPI, bool SP2>
; __device__ __forceinline__ void gemm_phase(LAS unsigned char* lds, const Sched2& S, const Epi& E) {
;     ...
;             PG8_WAIT_V(8); PG8_WAIT_L(0); PG8_BAR; PG8_MMA(0, 0, At, B0); PG8_MMA(0, 1, At, B1); PG8_BAR; PG8_SCHED;
;             PG8_LDA(At, 0, 1); PG8_STAGE(PG8_SB(0, 0), b2, voffB); PG8_STAGE(PG8_SB(0, 1), b2 + hstep, voffB); PG8_STAGE(PG8_SA(0, 0), a2, voffA);
;             PG8_WAIT_V(8); PG8_WAIT_L(0); PG8_BAR; PG8_MMA(1, 0, At, B0); PG8_MMA(1, 1, At, B1); PG8_BAR; PG8_SCHED;
;             PG8_LDB(B0, 1, 0); PG8_LDB(B1, 1, 1); PG8_SCHED; PG8_LDA(At, 1, 0); PG8_STAGE(PG8_SA(0, 1), a2 + hstep, voffA);
;             PG8_WAIT_V(8); PG8_WAIT_L(0); PG8_BAR; PG8_MMA(0, 0, At, B0); PG8_MMA(0, 1, At, B1); PG8_BAR; PG8_SCHED;
	s_setprio 1
	s_waitcnt lgkmcnt(0)
	v_mfma_f32_16x16x32_bf16 v[62:65], v[144:147], v[186:189], v[62:65]
	v_mfma_f32_16x16x32_bf16 v[58:61], v[162:165], v[186:189], v[58:61]
	v_mfma_f32_16x16x32_bf16 v[46:49], v[144:147], v[194:197], v[46:49]
	v_mfma_f32_16x16x32_bf16 v[42:45], v[162:165], v[194:197], v[42:45]
	v_mfma_f32_16x16x32_bf16 v[30:33], v[144:147], v[202:205], v[30:33]
	v_mfma_f32_16x16x32_bf16 v[26:29], v[162:165], v[202:205], v[26:29]
	v_mfma_f32_16x16x32_bf16 v[14:17], v[144:147], v[210:213], v[14:17]
	v_mfma_f32_16x16x32_bf16 v[10:13], v[162:165], v[210:213], v[10:13]
	v_mfma_f32_16x16x32_bf16 v[62:65], v[148:151], v[190:193], v[62:65]
	v_mfma_f32_16x16x32_bf16 v[58:61], v[166:169], v[190:193], v[58:61]
	v_mfma_f32_16x16x32_bf16 v[46:49], v[148:151], v[198:201], v[46:49]
	v_mfma_f32_16x16x32_bf16 v[42:45], v[166:169], v[198:201], v[42:45]
	v_mfma_f32_16x16x32_bf16 v[30:33], v[148:151], v[206:209], v[30:33]
	v_mfma_f32_16x16x32_bf16 v[26:29], v[166:169], v[206:209], v[26:29]
	v_mfma_f32_16x16x32_bf16 v[14:17], v[148:151], v[214:217], v[14:17]
	v_mfma_f32_16x16x32_bf16 v[10:13], v[166:169], v[214:217], v[10:13]
	s_setprio 0
	s_setprio 1
	v_mfma_f32_16x16x32_bf16 v[54:57], v[170:173], v[186:189], v[54:57]
	v_mfma_f32_16x16x32_bf16 v[50:53], v[178:181], v[186:189], v[50:53]
	v_mfma_f32_16x16x32_bf16 v[38:41], v[170:173], v[194:197], v[38:41]
	v_mfma_f32_16x16x32_bf16 v[34:37], v[178:181], v[194:197], v[34:37]
	v_mfma_f32_16x16x32_bf16 v[22:25], v[170:173], v[202:205], v[22:25]
	v_mfma_f32_16x16x32_bf16 v[18:21], v[178:181], v[202:205], v[18:21]
	v_mfma_f32_16x16x32_bf16 v[6:9], v[170:173], v[210:213], v[6:9]
	v_mfma_f32_16x16x32_bf16 v[2:5], v[178:181], v[210:213], v[2:5]
	v_mfma_f32_16x16x32_bf16 v[54:57], v[174:177], v[190:193], v[54:57]
	v_mfma_f32_16x16x32_bf16 v[50:53], v[182:185], v[190:193], v[50:53]
	v_mfma_f32_16x16x32_bf16 v[38:41], v[174:177], v[198:201], v[38:41]
	v_mfma_f32_16x16x32_bf16 v[34:37], v[182:185], v[198:201], v[34:37]
	v_mfma_f32_16x16x32_bf16 v[22:25], v[174:177], v[206:209], v[22:25]
	v_mfma_f32_16x16x32_bf16 v[18:21], v[182:185], v[206:209], v[18:21]
	v_mfma_f32_16x16x32_bf16 v[6:9], v[174:177], v[214:217], v[6:9]
	v_mfma_f32_16x16x32_bf16 v[2:5], v[182:185], v[214:217], v[2:5]
	s_setprio 0
	s_barrier
	s_add_i32 s71, 0, 0x18000
	v_add_u32_e32 v138, s71, v155
	s_add_i32 s94, 0, 0x1c000
	ds_read_b128 v[144:147], v138
	ds_read_b128 v[148:151], v138 offset:1024
	ds_read_b128 v[162:165], v138 offset:2048
	ds_read_b128 v[166:169], v138 offset:3072
	v_add_u32_e32 v138, s94, v155
	ds_read_b128 v[170:173], v138
	ds_read_b128 v[174:177], v138 offset:1024
	ds_read_b128 v[178:181], v138 offset:2048
	ds_read_b128 v[182:185], v138 offset:3072
	s_add_u32 s58, s76, 0x40000
	s_addc_u32 s59, s77, 0
	s_mov_b32 m0, s81
	v_lshl_add_u64 v[224:225], s[58:59], 0, v[130:131]
	ds_read_b128 v[186:189], v160 offset:32768
	ds_read_b128 v[190:193], v160 offset:33792
	ds_read_b128 v[194:197], v160 offset:34816
	ds_read_b128 v[198:201], v160 offset:35840
	ds_read_b128 v[202:205], v160 offset:36864
	ds_read_b128 v[206:209], v160 offset:37888
	ds_read_b128 v[210:213], v160 offset:38912
	ds_read_b128 v[214:217], v160 offset:39936
	global_load_lds_dwordx4 v[224:225], off
	v_lshl_add_u64 v[224:225], s[58:59], 0, v[134:135]
	s_mov_b32 m0, s82
	s_nop 0
	global_load_lds_dwordx4 v[224:225], off
	s_waitcnt vmcnt(8)
	s_waitcnt lgkmcnt(0)
	s_barrier
	s_setprio 1
	s_waitcnt lgkmcnt(0)
	v_mfma_f32_16x16x32_bf16 v[126:129], v[144:147], v[186:189], v[126:129]
	v_mfma_f32_16x16x32_bf16 v[122:125], v[162:165], v[186:189], v[122:125]
	v_mfma_f32_16x16x32_bf16 v[110:113], v[144:147], v[194:197], v[110:113]
	v_mfma_f32_16x16x32_bf16 v[106:109], v[162:165], v[194:197], v[106:109]
	v_mfma_f32_16x16x32_bf16 v[94:97], v[144:147], v[202:205], v[94:97]
	v_mfma_f32_16x16x32_bf16 v[90:93], v[162:165], v[202:205], v[90:93]
	v_mfma_f32_16x16x32_bf16 v[78:81], v[144:147], v[210:213], v[78:81]
	v_mfma_f32_16x16x32_bf16 v[74:77], v[162:165], v[210:213], v[74:77]
	v_mfma_f32_16x16x32_bf16 v[126:129], v[148:151], v[190:193], v[126:129]
	v_mfma_f32_16x16x32_bf16 v[122:125], v[166:169], v[190:193], v[122:125]
	v_mfma_f32_16x16x32_bf16 v[110:113], v[148:151], v[198:201], v[110:113]
	v_mfma_f32_16x16x32_bf16 v[106:109], v[166:169], v[198:201], v[106:109]
	v_mfma_f32_16x16x32_bf16 v[94:97], v[148:151], v[206:209], v[94:97]
	v_mfma_f32_16x16x32_bf16 v[90:93], v[166:169], v[206:209], v[90:93]
	v_mfma_f32_16x16x32_bf16 v[78:81], v[148:151], v[214:217], v[78:81]
	v_mfma_f32_16x16x32_bf16 v[74:77], v[166:169], v[214:217], v[74:77]
	s_setprio 0
	s_setprio 1
	v_mfma_f32_16x16x32_bf16 v[118:121], v[170:173], v[186:189], v[118:121]
	v_mfma_f32_16x16x32_bf16 v[114:117], v[178:181], v[186:189], v[114:117]
	v_mfma_f32_16x16x32_bf16 v[102:105], v[170:173], v[194:197], v[102:105]
	v_mfma_f32_16x16x32_bf16 v[98:101], v[178:181], v[194:197], v[98:101]
	v_mfma_f32_16x16x32_bf16 v[86:89], v[170:173], v[202:205], v[86:89]
	v_mfma_f32_16x16x32_bf16 v[82:85], v[178:181], v[202:205], v[82:85]
	v_mfma_f32_16x16x32_bf16 v[70:73], v[170:173], v[210:213], v[70:73]
	v_mfma_f32_16x16x32_bf16 v[66:69], v[178:181], v[210:213], v[66:69]
	v_mfma_f32_16x16x32_bf16 v[118:121], v[174:177], v[190:193], v[118:121]
	v_mfma_f32_16x16x32_bf16 v[114:117], v[182:185], v[190:193], v[114:117]
	v_mfma_f32_16x16x32_bf16 v[102:105], v[174:177], v[198:201], v[102:105]
	v_mfma_f32_16x16x32_bf16 v[98:101], v[182:185], v[198:201], v[98:101]
	v_mfma_f32_16x16x32_bf16 v[86:89], v[174:177], v[206:209], v[86:89]
	v_mfma_f32_16x16x32_bf16 v[82:85], v[182:185], v[206:209], v[82:85]
	v_mfma_f32_16x16x32_bf16 v[70:73], v[174:177], v[214:217], v[70:73]
	v_mfma_f32_16x16x32_bf16 v[66:69], v[182:185], v[214:217], v[66:69]
	s_setprio 0
	s_barrier
; #define PG8_STAGE(bufoff, gbase, voff) do { _Pragma("unroll") for (int _i = 0; _i < 2; ++_i) \
;         __builtin_amdgcn_global_load_lds((const unsigned*)((const char*)(gbase) + (voff)[_i]), (LAS unsigned*)(lds + (bufoff) + ldsw + _i * 8192), 16, 0, 0); } while (0)
; #define PG8_LDA(dst, b, h) do { _Pragma("unroll") for (int m = 0; m < 4; ++m) _Pragma("unroll") for (int k = 0; k < 2; ++k) dst[m][k] = *(const LAS bf16x8*)(lds + PG8_SA(b, h) + aoff + m * 2048 + k * 1024); } while (0)
; #define PG8_LDB(dst, b, h) do { _Pragma("unroll") for (int n = 0; n < 2; ++n) _Pragma("unroll") for (int k = 0; k < 2; ++k) dst[n][k] = *(const LAS bf16x8*)(lds + PG8_SB(b, h) + boff + n * 2048 + k * 1024); } while (0)
; #define PG8_MMA(ai, bj, At, Bt) do { __builtin_amdgcn_s_setprio(1); _Pragma("unroll") for (int m = 0; m < 4; ++m) _Pragma("unroll") for (int n = 0; n < 2; ++n) _Pragma("unroll") for (int k = 0; k < 2; ++k) \
;         acc[ai][bj][m][n] = __builtin_amdgcn_mfma_f32_16x16x32_bf16(Bt[n][k], At[m][k], acc[ai][bj][m][n], 0, 0, 0); __builtin_amdgcn_s_setprio(0); } while (0)
; #define PG8_WAIT_V(n) asm volatile("s_waitcnt vmcnt(" #n ")" ::: "memory")
; #define PG8_WAIT_L(n) asm volatile("s_waitcnt lgkmcnt(" #n ")" ::: "memory")
; #define PG8_BAR __builtin_amdgcn_s_barrier()
; #define PG8_SCHED __builtin_amdgcn_sched_barrier(0)
; template <class Epi, bool ALIGN_EPI, bool SP2>
; __device__ __forceinline__ void gemm_phase(LAS unsigned char* lds, const Sched2& S, const Epi& E) {
;     ...
;         for (int t = 0; t < nt; t += 2) {
;     ...
;             PG8_LDB(B0, 1, 0); PG8_LDB(B1, 1, 1); PG8_SCHED; PG8_LDA(At, 1, 0); PG8_STAGE(PG8_SA(0, 1), a2 + hstep, voffA);
;             PG8_WAIT_V(8); PG8_WAIT_L(0); PG8_BAR; PG8_MMA(0, 0, At, B0); PG8_MMA(0, 1, At, B1); PG8_BAR; PG8_SCHED;
;             PG8_LDA(At, 1, 1); PG8_STAGE(PG8_SB(1, 0), b3, voffB); PG8_STAGE(PG8_SB(1, 1), b3 + hstep, voffB); PG8_STAGE(PG8_SA(1, 0), a3, voffA);
;             PG8_WAIT_V(8); PG8_WAIT_L(0); PG8_BAR; PG8_MMA(1, 0, At, B0); PG8_MMA(1, 1, At, B1); PG8_BAR; PG8_SCHED;
	s_add_i32 s58, s71, s35
	v_lshl_add_u64 v[152:153], v[152:153], 0, s[18:19]
	s_mov_b32 m0, s58
	ds_read_b128 v[186:189], v160 offset:49152
	ds_read_b128 v[190:193], v160 offset:50176
	ds_read_b128 v[194:197], v160 offset:51200
	ds_read_b128 v[198:201], v160 offset:52224
	ds_read_b128 v[202:205], v160 offset:53248
	ds_read_b128 v[206:209], v160 offset:54272
	ds_read_b128 v[210:213], v160 offset:55296
	ds_read_b128 v[214:217], v160 offset:56320
	global_load_lds_dwordx4 v[152:153], off
	s_add_i32 m0, s58, 0x2000
	s_add_u32 s58, s74, 0x40080
	v_lshl_add_u64 v[152:153], v[218:219], 0, s[18:19]
	s_addc_u32 s59, s75, 0
	s_add_i32 s71, s94, s35
	global_load_lds_dwordx4 v[152:153], off
	v_lshl_add_u64 v[152:153], s[58:59], 0, v[132:133]
	s_mov_b32 m0, s71
	s_nop 0
	global_load_lds_dwordx4 v[152:153], off
	v_lshl_add_u64 v[152:153], s[58:59], 0, v[136:137]
	s_add_i32 m0, s71, 0x2000
	s_nop 0
	global_load_lds_dwordx4 v[152:153], off
	v_lshl_add_u64 v[152:153], v[220:221], 0, s[18:19]
	s_mov_b32 m0, s85
	s_nop 0
	global_load_lds_dwordx4 v[152:153], off
	v_lshl_add_u64 v[152:153], v[222:223], 0, s[18:19]
	s_mov_b32 m0, s86
	s_nop 0
	global_load_lds_dwordx4 v[152:153], off
	s_waitcnt vmcnt(8)
	s_waitcnt lgkmcnt(0)
	s_barrier
	s_setprio 1
	s_waitcnt lgkmcnt(0)
	v_mfma_f32_16x16x32_bf16 v[62:65], v[144:147], v[186:189], v[62:65]
	v_mfma_f32_16x16x32_bf16 v[58:61], v[162:165], v[186:189], v[58:61]
	v_mfma_f32_16x16x32_bf16 v[46:49], v[144:147], v[194:197], v[46:49]
	v_mfma_f32_16x16x32_bf16 v[42:45], v[162:165], v[194:197], v[42:45]
	v_mfma_f32_16x16x32_bf16 v[30:33], v[144:147], v[202:205], v[30:33]
	v_mfma_f32_16x16x32_bf16 v[26:29], v[162:165], v[202:205], v[26:29]
	v_mfma_f32_16x16x32_bf16 v[14:17], v[144:147], v[210:213], v[14:17]
	v_mfma_f32_16x16x32_bf16 v[10:13], v[162:165], v[210:213], v[10:13]
	v_mfma_f32_16x16x32_bf16 v[62:65], v[148:151], v[190:193], v[62:65]
	v_mfma_f32_16x16x32_bf16 v[58:61], v[166:169], v[190:193], v[58:61]
	v_mfma_f32_16x16x32_bf16 v[46:49], v[148:151], v[198:201], v[46:49]
	v_mfma_f32_16x16x32_bf16 v[42:45], v[166:169], v[198:201], v[42:45]
	v_mfma_f32_16x16x32_bf16 v[30:33], v[148:151], v[206:209], v[30:33]
	v_mfma_f32_16x16x32_bf16 v[26:29], v[166:169], v[206:209], v[26:29]
	v_mfma_f32_16x16x32_bf16 v[14:17], v[148:151], v[214:217], v[14:17]
	v_mfma_f32_16x16x32_bf16 v[10:13], v[166:169], v[214:217], v[10:13]
	s_setprio 0
	s_setprio 1
	v_mfma_f32_16x16x32_bf16 v[54:57], v[170:173], v[186:189], v[54:57]
	v_mfma_f32_16x16x32_bf16 v[50:53], v[178:181], v[186:189], v[50:53]
	v_mfma_f32_16x16x32_bf16 v[38:41], v[170:173], v[194:197], v[38:41]
	v_mfma_f32_16x16x32_bf16 v[34:37], v[178:181], v[194:197], v[34:37]
	v_mfma_f32_16x16x32_bf16 v[22:25], v[170:173], v[202:205], v[22:25]
	v_mfma_f32_16x16x32_bf16 v[18:21], v[178:181], v[202:205], v[18:21]
	v_mfma_f32_16x16x32_bf16 v[6:9], v[170:173], v[210:213], v[6:9]
	v_mfma_f32_16x16x32_bf16 v[2:5], v[178:181], v[210:213], v[2:5]
	v_mfma_f32_16x16x32_bf16 v[54:57], v[174:177], v[190:193], v[54:57]
	v_mfma_f32_16x16x32_bf16 v[50:53], v[182:185], v[190:193], v[50:53]
	v_mfma_f32_16x16x32_bf16 v[38:41], v[174:177], v[198:201], v[38:41]
	v_mfma_f32_16x16x32_bf16 v[34:37], v[182:185], v[198:201], v[34:37]
	v_mfma_f32_16x16x32_bf16 v[22:25], v[174:177], v[206:209], v[22:25]
	v_mfma_f32_16x16x32_bf16 v[18:21], v[182:185], v[206:209], v[18:21]
	v_mfma_f32_16x16x32_bf16 v[6:9], v[174:177], v[214:217], v[6:9]
	v_mfma_f32_16x16x32_bf16 v[2:5], v[182:185], v[214:217], v[2:5]
	s_setprio 0
	s_add_i32 s43, s43, 2
	s_add_u32 s72, s72, 0x100
	s_addc_u32 s73, s73, 0
	s_add_u32 s1, s1, 0x100
	s_addc_u32 s41, s41, 0
	s_cmp_gt_u32 s43, 13
	s_barrier
	s_cbranch_scc0 .LBB0_190
	s_and_b64 vcc, exec, s[22:23]
	s_cbranch_vccz .LBB0_193
	s_barrier

; #define PG8_STAGE(bufoff, gbase, voff) do { _Pragma("unroll") for (int _i = 0; _i < 2; ++_i) \
;         __builtin_amdgcn_global_load_lds((const unsigned*)((const char*)(gbase) + (voff)[_i]), (LAS unsigned*)(lds + (bufoff) + ldsw + _i * 8192), 16, 0, 0); } while (0)
; #define PG8_LDA(dst, b, h) do { _Pragma("unroll") for (int m = 0; m < 4; ++m) _Pragma("unroll") for (int k = 0; k < 2; ++k) dst[m][k] = *(const LAS bf16x8*)(lds + PG8_SA(b, h) + aoff + m * 2048 + k * 1024); } while (0)
; #define PG8_LDB(dst, b, h) do { _Pragma("unroll") for (int n = 0; n < 2; ++n) _Pragma("unroll") for (int k = 0; k < 2; ++k) dst[n][k] = *(const LAS bf16x8*)(lds + PG8_SB(b, h) + boff + n * 2048 + k * 1024); } while (0)
; #define PG8_MMA(ai, bj, At, Bt) do { __builtin_amdgcn_s_setprio(1); _Pragma("unroll") for (int m = 0; m < 4; ++m) _Pragma("unroll") for (int n = 0; n < 2; ++n) _Pragma("unroll") for (int k = 0; k < 2; ++k) \
;         acc[ai][bj][m][n] = __builtin_amdgcn_mfma_f32_16x16x32_bf16(Bt[n][k], At[m][k], acc[ai][bj][m][n], 0, 0, 0); __builtin_amdgcn_s_setprio(0); } while (0)
; #define PG8_WAIT_V(n) asm volatile("s_waitcnt vmcnt(" #n ")" ::: "memory")
; #define PG8_WAIT_L(n) asm volatile("s_waitcnt lgkmcnt(" #n ")" ::: "memory")
; #define PG8_BAR __builtin_amdgcn_s_barrier()
; #define PG8_SCHED __builtin_amdgcn_sched_barrier(0)
; template <class Epi, bool ALIGN_EPI, bool SP2>
; __device__ __forceinline__ void gemm_phase(LAS unsigned char* lds, const Sched2& S, const Epi& E) {
;     ...
;         for (int t = 0; t < nt; t += 2) {
;             const bool last = (t == nt - 2);
;             const char* a1 = cA + (size_t)(t + 1) * kstep;
;             const char* a2 = last ? nA : cA + (size_t)(t + 2) * kstep; const char* b2 = last ? nB : cB + (size_t)(t + 2) * kstep;
;             const char* a3 = a2 + kstep; const char* b3 = b2 + kstep;
;             if constexpr (SP2) {
;             PG8_LDB(B0, 0, 0); PG8_LDB(B1, 0, 1); PG8_SCHED; PG8_LDA(At, 0, 0); PG8_STAGE(PG8_SA(1, 1), a1 + hstep, voffA);
;             PG8_WAIT_V(8); PG8_WAIT_L(0); PG8_BAR; PG8_MMA(0, 0, At, B0); PG8_MMA(0, 1, At, B1); PG8_BAR; PG8_SCHED;
;             PG8_LDA(At, 0, 1); PG8_STAGE(PG8_SB(0, 0), b2, voffB); PG8_STAGE(PG8_SB(0, 1), b2 + hstep, voffB); PG8_STAGE(PG8_SA(0, 0), a2, voffA);
;             PG8_WAIT_V(8); PG8_WAIT_L(0); PG8_BAR; PG8_MMA(1, 0, At, B0); PG8_MMA(1, 1, At, B1); PG8_BAR; PG8_SCHED;
.LBB0_362:
	ds_read_b128 v[82:85], v192
	ds_read_b128 v[90:93], v192 offset:1024
	ds_read_b128 v[98:101], v192 offset:2048
	ds_read_b128 v[102:105], v192 offset:3072
	ds_read_b128 v[146:149], v193
	ds_read_b128 v[150:153], v193 offset:1024
	ds_read_b128 v[154:157], v193 offset:2048
	ds_read_b128 v[158:161], v193 offset:3072
	s_add_u32 s42, s40, 0xfff80080
	s_addc_u32 s43, s41, -1
	s_cmp_eq_u32 s39, 28
	s_cselect_b32 s49, s35, s43
	s_cselect_b32 s48, s34, s42
	s_cselect_b32 s43, s37, s31
	s_cselect_b32 s42, s36, s29
	v_lshl_add_u64 v[212:213], s[40:41], 0, v[170:171]
	s_add_i32 m0, s67, 0xc000
	ds_read_b128 v[174:177], v194
	ds_read_b128 v[178:181], v194 offset:1024
	ds_read_b128 v[182:185], v194 offset:2048
	ds_read_b128 v[186:189], v194 offset:3072
	ds_read_b128 v[196:199], v194 offset:4096
	ds_read_b128 v[200:203], v194 offset:5120
	ds_read_b128 v[204:207], v194 offset:6144
	ds_read_b128 v[208:211], v194 offset:7168
	global_load_lds_dwordx4 v[212:213], off
	v_lshl_add_u64 v[212:213], s[40:41], 0, v[172:173]
	s_add_i32 m0, s67, 0xe000
	s_nop 0
	global_load_lds_dwordx4 v[212:213], off
	s_waitcnt vmcnt(8)
	s_waitcnt lgkmcnt(0)
	s_barrier
	s_setprio 1
	s_waitcnt lgkmcnt(0)
	v_mfma_f32_16x16x32_bf16 v[142:145], v[82:85], v[174:177], v[142:145]
	v_mfma_f32_16x16x32_bf16 v[138:141], v[98:101], v[174:177], v[138:141]
	v_mfma_f32_16x16x32_bf16 v[126:129], v[82:85], v[182:185], v[126:129]
	v_mfma_f32_16x16x32_bf16 v[122:125], v[98:101], v[182:185], v[122:125]
	v_mfma_f32_16x16x32_bf16 v[110:113], v[82:85], v[196:199], v[110:113]
	v_mfma_f32_16x16x32_bf16 v[106:109], v[98:101], v[196:199], v[106:109]
	v_mfma_f32_16x16x32_bf16 v[78:81], v[82:85], v[204:207], v[78:81]
	v_mfma_f32_16x16x32_bf16 v[74:77], v[98:101], v[204:207], v[74:77]
	v_mfma_f32_16x16x32_bf16 v[142:145], v[90:93], v[178:181], v[142:145]
	v_mfma_f32_16x16x32_bf16 v[138:141], v[102:105], v[178:181], v[138:141]
	v_mfma_f32_16x16x32_bf16 v[126:129], v[90:93], v[186:189], v[126:129]
	v_mfma_f32_16x16x32_bf16 v[122:125], v[102:105], v[186:189], v[122:125]
	v_mfma_f32_16x16x32_bf16 v[110:113], v[90:93], v[200:203], v[110:113]
	v_mfma_f32_16x16x32_bf16 v[106:109], v[102:105], v[200:203], v[106:109]
	v_mfma_f32_16x16x32_bf16 v[78:81], v[90:93], v[208:211], v[78:81]
	v_mfma_f32_16x16x32_bf16 v[74:77], v[102:105], v[208:211], v[74:77]
	s_setprio 0
	s_setprio 1
	v_mfma_f32_16x16x32_bf16 v[134:137], v[146:149], v[174:177], v[134:137]
	v_mfma_f32_16x16x32_bf16 v[130:133], v[154:157], v[174:177], v[130:133]
	v_mfma_f32_16x16x32_bf16 v[118:121], v[146:149], v[182:185], v[118:121]
	v_mfma_f32_16x16x32_bf16 v[114:117], v[154:157], v[182:185], v[114:117]
	v_mfma_f32_16x16x32_bf16 v[94:97], v[146:149], v[196:199], v[94:97]
	v_mfma_f32_16x16x32_bf16 v[86:89], v[154:157], v[196:199], v[86:89]
	v_mfma_f32_16x16x32_bf16 v[70:73], v[146:149], v[204:207], v[70:73]
	v_mfma_f32_16x16x32_bf16 v[66:69], v[154:157], v[204:207], v[66:69]
	v_mfma_f32_16x16x32_bf16 v[134:137], v[150:153], v[178:181], v[134:137]
	v_mfma_f32_16x16x32_bf16 v[130:133], v[158:161], v[178:181], v[130:133]
	v_mfma_f32_16x16x32_bf16 v[118:121], v[150:153], v[186:189], v[118:121]
	v_mfma_f32_16x16x32_bf16 v[114:117], v[158:161], v[186:189], v[114:117]
	v_mfma_f32_16x16x32_bf16 v[94:97], v[150:153], v[200:203], v[94:97]
	v_mfma_f32_16x16x32_bf16 v[86:89], v[158:161], v[200:203], v[86:89]
	v_mfma_f32_16x16x32_bf16 v[70:73], v[150:153], v[208:211], v[70:73]
	v_mfma_f32_16x16x32_bf16 v[66:69], v[158:161], v[208:211], v[66:69]
	s_setprio 0
	s_barrier
	s_add_i32 s58, s79, s66
	v_lshl_add_u64 v[212:213], s[42:43], 0, v[164:165]
	s_mov_b32 m0, s58
	ds_read_b128 v[174:177], v194 offset:16384
	ds_read_b128 v[178:181], v194 offset:17408
	ds_read_b128 v[182:185], v194 offset:18432
	ds_read_b128 v[186:189], v194 offset:19456
	ds_read_b128 v[196:199], v194 offset:20480
	ds_read_b128 v[200:203], v194 offset:21504
	ds_read_b128 v[204:207], v194 offset:22528
	ds_read_b128 v[208:211], v194 offset:23552
	global_load_lds_dwordx4 v[212:213], off
	s_add_i32 m0, s58, 0x2000
	s_add_u32 s58, s42, 0x80000
	v_lshl_add_u64 v[214:215], s[42:43], 0, v[168:169]
	s_addc_u32 s59, s43, 0
	s_add_i32 s82, s80, s66
	global_load_lds_dwordx4 v[214:215], off
	v_lshl_add_u64 v[216:217], s[58:59], 0, v[164:165]
	s_mov_b32 m0, s82
	v_lshl_add_u64 v[218:219], s[48:49], 0, v[166:167]
	global_load_lds_dwordx4 v[216:217], off
	v_lshl_add_u64 v[216:217], s[58:59], 0, v[168:169]
	s_add_i32 m0, s82, 0x2000
	s_nop 0
	global_load_lds_dwordx4 v[216:217], off
	v_lshl_add_u64 v[216:217], s[48:49], 0, v[162:163]
	s_mov_b32 m0, s67
	s_nop 0
	global_load_lds_dwordx4 v[216:217], off
	s_mov_b32 m0, s68
	s_nop 0
	global_load_lds_dwordx4 v[218:219], off
	s_waitcnt vmcnt(8)
	s_waitcnt lgkmcnt(0)
	s_barrier
; #define PG8_STAGE(bufoff, gbase, voff) do { _Pragma("unroll") for (int _i = 0; _i < 2; ++_i) \
;         __builtin_amdgcn_global_load_lds((const unsigned*)((const char*)(gbase) + (voff)[_i]), (LAS unsigned*)(lds + (bufoff) + ldsw + _i * 8192), 16, 0, 0); } while (0)
; #define PG8_LDA(dst, b, h) do { _Pragma("unroll") for (int m = 0; m < 4; ++m) _Pragma("unroll") for (int k = 0; k < 2; ++k) dst[m][k] = *(const LAS bf16x8*)(lds + PG8_SA(b, h) + aoff + m * 2048 + k * 1024); } while (0)
; #define PG8_LDB(dst, b, h) do { _Pragma("unroll") for (int n = 0; n < 2; ++n) _Pragma("unroll") for (int k = 0; k < 2; ++k) dst[n][k] = *(const LAS bf16x8*)(lds + PG8_SB(b, h) + boff + n * 2048 + k * 1024); } while (0)
; #define PG8_MMA(ai, bj, At, Bt) do { __builtin_amdgcn_s_setprio(1); _Pragma("unroll") for (int m = 0; m < 4; ++m) _Pragma("unroll") for (int n = 0; n < 2; ++n) _Pragma("unroll") for (int k = 0; k < 2; ++k) \
;         acc[ai][bj][m][n] = __builtin_amdgcn_mfma_f32_16x16x32_bf16(Bt[n][k], At[m][k], acc[ai][bj][m][n], 0, 0, 0); __builtin_amdgcn_s_setprio(0); } while (0)
; #define PG8_WAIT_V(n) asm volatile("s_waitcnt vmcnt(" #n ")" ::: "memory")
; #define PG8_WAIT_L(n) asm volatile("s_waitcnt lgkmcnt(" #n ")" ::: "memory")
; #define PG8_BAR __builtin_amdgcn_s_barrier()
; #define PG8_SCHED __builtin_amdgcn_sched_barrier(0)
; template <class Epi, bool ALIGN_EPI, bool SP2>
; __device__ __forceinline__ void gemm_phase(LAS unsigned char* lds, const Sched2& S, const Epi& E) {
;     ...
;             PG8_WAIT_V(8); PG8_WAIT_L(0); PG8_BAR; PG8_MMA(0, 0, At, B0); PG8_MMA(0, 1, At, B1); PG8_BAR; PG8_SCHED;
;             PG8_LDA(At, 0, 1); PG8_STAGE(PG8_SB(0, 0), b2, voffB); PG8_STAGE(PG8_SB(0, 1), b2 + hstep, voffB); PG8_STAGE(PG8_SA(0, 0), a2, voffA);
;             PG8_WAIT_V(8); PG8_WAIT_L(0); PG8_BAR; PG8_MMA(1, 0, At, B0); PG8_MMA(1, 1, At, B1); PG8_BAR; PG8_SCHED;
;             PG8_LDB(B0, 1, 0); PG8_LDB(B1, 1, 1); PG8_SCHED; PG8_LDA(At, 1, 0); PG8_STAGE(PG8_SA(0, 1), a2 + hstep, voffA);
;             PG8_WAIT_V(8); PG8_WAIT_L(0); PG8_BAR; PG8_MMA(0, 0, At, B0); PG8_MMA(0, 1, At, B1); PG8_BAR; PG8_SCHED;
	s_setprio 1
	s_waitcnt lgkmcnt(0)
	v_mfma_f32_16x16x32_bf16 v[62:65], v[82:85], v[174:177], v[62:65]
	v_mfma_f32_16x16x32_bf16 v[58:61], v[98:101], v[174:177], v[58:61]
	v_mfma_f32_16x16x32_bf16 v[46:49], v[82:85], v[182:185], v[46:49]
	v_mfma_f32_16x16x32_bf16 v[42:45], v[98:101], v[182:185], v[42:45]
	v_mfma_f32_16x16x32_bf16 v[30:33], v[82:85], v[196:199], v[30:33]
	v_mfma_f32_16x16x32_bf16 v[26:29], v[98:101], v[196:199], v[26:29]
	v_mfma_f32_16x16x32_bf16 v[14:17], v[82:85], v[204:207], v[14:17]
	v_mfma_f32_16x16x32_bf16 v[10:13], v[98:101], v[204:207], v[10:13]
	v_mfma_f32_16x16x32_bf16 v[62:65], v[90:93], v[178:181], v[62:65]
	v_mfma_f32_16x16x32_bf16 v[58:61], v[102:105], v[178:181], v[58:61]
	v_mfma_f32_16x16x32_bf16 v[46:49], v[90:93], v[186:189], v[46:49]
	v_mfma_f32_16x16x32_bf16 v[42:45], v[102:105], v[186:189], v[42:45]
	v_mfma_f32_16x16x32_bf16 v[30:33], v[90:93], v[200:203], v[30:33]
	v_mfma_f32_16x16x32_bf16 v[26:29], v[102:105], v[200:203], v[26:29]
	v_mfma_f32_16x16x32_bf16 v[14:17], v[90:93], v[208:211], v[14:17]
	v_mfma_f32_16x16x32_bf16 v[10:13], v[102:105], v[208:211], v[10:13]
	s_setprio 0
	s_setprio 1
	v_mfma_f32_16x16x32_bf16 v[54:57], v[146:149], v[174:177], v[54:57]
	v_mfma_f32_16x16x32_bf16 v[50:53], v[154:157], v[174:177], v[50:53]
	v_mfma_f32_16x16x32_bf16 v[38:41], v[146:149], v[182:185], v[38:41]
	v_mfma_f32_16x16x32_bf16 v[34:37], v[154:157], v[182:185], v[34:37]
	v_mfma_f32_16x16x32_bf16 v[22:25], v[146:149], v[196:199], v[22:25]
	v_mfma_f32_16x16x32_bf16 v[18:21], v[154:157], v[196:199], v[18:21]
	v_mfma_f32_16x16x32_bf16 v[6:9], v[146:149], v[204:207], v[6:9]
	v_mfma_f32_16x16x32_bf16 v[2:5], v[154:157], v[204:207], v[2:5]
	v_mfma_f32_16x16x32_bf16 v[54:57], v[150:153], v[178:181], v[54:57]
	v_mfma_f32_16x16x32_bf16 v[50:53], v[158:161], v[178:181], v[50:53]
	v_mfma_f32_16x16x32_bf16 v[38:41], v[150:153], v[186:189], v[38:41]
	v_mfma_f32_16x16x32_bf16 v[34:37], v[158:161], v[186:189], v[34:37]
	v_mfma_f32_16x16x32_bf16 v[22:25], v[150:153], v[200:203], v[22:25]
	v_mfma_f32_16x16x32_bf16 v[18:21], v[158:161], v[200:203], v[18:21]
	v_mfma_f32_16x16x32_bf16 v[6:9], v[150:153], v[208:211], v[6:9]
	v_mfma_f32_16x16x32_bf16 v[2:5], v[158:161], v[208:211], v[2:5]
	s_setprio 0
	s_barrier
	s_add_i32 s58, 0, 0x18000
	s_add_i32 s59, 0, 0x1c000
	v_add_u32_e32 v102, s58, v190
	v_add_u32_e32 v158, s59, v190
	ds_read_b128 v[82:85], v102
	ds_read_b128 v[90:93], v102 offset:1024
	ds_read_b128 v[98:101], v102 offset:2048
	ds_read_b128 v[102:105], v102 offset:3072
	ds_read_b128 v[146:149], v158
	ds_read_b128 v[150:153], v158 offset:1024
	ds_read_b128 v[154:157], v158 offset:2048
	ds_read_b128 v[158:161], v158 offset:3072
	s_add_u32 s48, s48, 0x80000
	s_addc_u32 s49, s49, 0
	s_mov_b32 m0, s69
	v_lshl_add_u64 v[220:221], s[48:49], 0, v[162:163]
	ds_read_b128 v[174:177], v194 offset:32768
	ds_read_b128 v[178:181], v194 offset:33792
	ds_read_b128 v[182:185], v194 offset:34816
	ds_read_b128 v[186:189], v194 offset:35840
	ds_read_b128 v[196:199], v194 offset:36864
	ds_read_b128 v[200:203], v194 offset:37888
	ds_read_b128 v[204:207], v194 offset:38912
	ds_read_b128 v[208:211], v194 offset:39936
	global_load_lds_dwordx4 v[220:221], off
	v_lshl_add_u64 v[220:221], s[48:49], 0, v[166:167]
	s_mov_b32 m0, s70
	s_nop 0
	global_load_lds_dwordx4 v[220:221], off
	s_waitcnt vmcnt(8)
	s_waitcnt lgkmcnt(0)
	s_barrier
	s_setprio 1
	s_waitcnt lgkmcnt(0)
	v_mfma_f32_16x16x32_bf16 v[142:145], v[82:85], v[174:177], v[142:145]
	v_mfma_f32_16x16x32_bf16 v[138:141], v[98:101], v[174:177], v[138:141]
	v_mfma_f32_16x16x32_bf16 v[126:129], v[82:85], v[182:185], v[126:129]
	v_mfma_f32_16x16x32_bf16 v[122:125], v[98:101], v[182:185], v[122:125]
	v_mfma_f32_16x16x32_bf16 v[110:113], v[82:85], v[196:199], v[110:113]
	v_mfma_f32_16x16x32_bf16 v[106:109], v[98:101], v[196:199], v[106:109]
	v_mfma_f32_16x16x32_bf16 v[78:81], v[82:85], v[204:207], v[78:81]
	v_mfma_f32_16x16x32_bf16 v[74:77], v[98:101], v[204:207], v[74:77]
	v_mfma_f32_16x16x32_bf16 v[142:145], v[90:93], v[178:181], v[142:145]
	v_mfma_f32_16x16x32_bf16 v[138:141], v[102:105], v[178:181], v[138:141]
	v_mfma_f32_16x16x32_bf16 v[126:129], v[90:93], v[186:189], v[126:129]
	v_mfma_f32_16x16x32_bf16 v[122:125], v[102:105], v[186:189], v[122:125]
	v_mfma_f32_16x16x32_bf16 v[110:113], v[90:93], v[200:203], v[110:113]
	v_mfma_f32_16x16x32_bf16 v[106:109], v[102:105], v[200:203], v[106:109]
	v_mfma_f32_16x16x32_bf16 v[78:81], v[90:93], v[208:211], v[78:81]
	v_mfma_f32_16x16x32_bf16 v[74:77], v[102:105], v[208:211], v[74:77]
	s_setprio 0
	s_setprio 1
	v_mfma_f32_16x16x32_bf16 v[134:137], v[146:149], v[174:177], v[134:137]
	v_mfma_f32_16x16x32_bf16 v[130:133], v[154:157], v[174:177], v[130:133]
	v_mfma_f32_16x16x32_bf16 v[118:121], v[146:149], v[182:185], v[118:121]
	v_mfma_f32_16x16x32_bf16 v[114:117], v[154:157], v[182:185], v[114:117]
	v_mfma_f32_16x16x32_bf16 v[94:97], v[146:149], v[196:199], v[94:97]
	v_mfma_f32_16x16x32_bf16 v[86:89], v[154:157], v[196:199], v[86:89]
	v_mfma_f32_16x16x32_bf16 v[70:73], v[146:149], v[204:207], v[70:73]
	v_mfma_f32_16x16x32_bf16 v[66:69], v[154:157], v[204:207], v[66:69]
	v_mfma_f32_16x16x32_bf16 v[134:137], v[150:153], v[178:181], v[134:137]
	v_mfma_f32_16x16x32_bf16 v[130:133], v[158:161], v[178:181], v[130:133]
	v_mfma_f32_16x16x32_bf16 v[118:121], v[150:153], v[186:189], v[118:121]
	v_mfma_f32_16x16x32_bf16 v[114:117], v[158:161], v[186:189], v[114:117]
	v_mfma_f32_16x16x32_bf16 v[94:97], v[150:153], v[200:203], v[94:97]
	v_mfma_f32_16x16x32_bf16 v[86:89], v[158:161], v[200:203], v[86:89]
	v_mfma_f32_16x16x32_bf16 v[70:73], v[150:153], v[208:211], v[70:73]
	v_mfma_f32_16x16x32_bf16 v[66:69], v[158:161], v[208:211], v[66:69]
	s_setprio 0
	s_barrier
; #define PG8_STAGE(bufoff, gbase, voff) do { _Pragma("unroll") for (int _i = 0; _i < 2; ++_i) \
;         __builtin_amdgcn_global_load_lds((const unsigned*)((const char*)(gbase) + (voff)[_i]), (LAS unsigned*)(lds + (bufoff) + ldsw + _i * 8192), 16, 0, 0); } while (0)
; #define PG8_LDA(dst, b, h) do { _Pragma("unroll") for (int m = 0; m < 4; ++m) _Pragma("unroll") for (int k = 0; k < 2; ++k) dst[m][k] = *(const LAS bf16x8*)(lds + PG8_SA(b, h) + aoff + m * 2048 + k * 1024); } while (0)
; #define PG8_LDB(dst, b, h) do { _Pragma("unroll") for (int n = 0; n < 2; ++n) _Pragma("unroll") for (int k = 0; k < 2; ++k) dst[n][k] = *(const LAS bf16x8*)(lds + PG8_SB(b, h) + boff + n * 2048 + k * 1024); } while (0)
; #define PG8_MMA(ai, bj, At, Bt) do { __builtin_amdgcn_s_setprio(1); _Pragma("unroll") for (int m = 0; m < 4; ++m) _Pragma("unroll") for (int n = 0; n < 2; ++n) _Pragma("unroll") for (int k = 0; k < 2; ++k) \
;         acc[ai][bj][m][n] = __builtin_amdgcn_mfma_f32_16x16x32_bf16(Bt[n][k], At[m][k], acc[ai][bj][m][n], 0, 0, 0); __builtin_amdgcn_s_setprio(0); } while (0)
; #define PG8_WAIT_V(n) asm volatile("s_waitcnt vmcnt(" #n ")" ::: "memory")
; #define PG8_WAIT_L(n) asm volatile("s_waitcnt lgkmcnt(" #n ")" ::: "memory")
; #define PG8_BAR __builtin_amdgcn_s_barrier()
; #define PG8_SCHED __builtin_amdgcn_sched_barrier(0)
; template <class Epi, bool ALIGN_EPI, bool SP2>
; __device__ __forceinline__ void gemm_phase(LAS unsigned char* lds, const Sched2& S, const Epi& E) {
;     ...
;         for (int t = 0; t < nt; t += 2) {
;     ...
;             PG8_LDB(B0, 1, 0); PG8_LDB(B1, 1, 1); PG8_SCHED; PG8_LDA(At, 1, 0); PG8_STAGE(PG8_SA(0, 1), a2 + hstep, voffA);
;             PG8_WAIT_V(8); PG8_WAIT_L(0); PG8_BAR; PG8_MMA(0, 0, At, B0); PG8_MMA(0, 1, At, B1); PG8_BAR; PG8_SCHED;
;             PG8_LDA(At, 1, 1); PG8_STAGE(PG8_SB(1, 0), b3, voffB); PG8_STAGE(PG8_SB(1, 1), b3 + hstep, voffB); PG8_STAGE(PG8_SA(1, 0), a3, voffA);
;             PG8_WAIT_V(8); PG8_WAIT_L(0); PG8_BAR; PG8_MMA(1, 0, At, B0); PG8_MMA(1, 1, At, B1); PG8_BAR; PG8_SCHED;
	s_add_i32 s48, s58, s66
	v_lshl_add_u64 v[212:213], v[212:213], 0, s[22:23]
	s_mov_b32 m0, s48
	ds_read_b128 v[174:177], v194 offset:49152
	ds_read_b128 v[178:181], v194 offset:50176
	ds_read_b128 v[182:185], v194 offset:51200
	ds_read_b128 v[186:189], v194 offset:52224
	ds_read_b128 v[196:199], v194 offset:53248
	ds_read_b128 v[200:203], v194 offset:54272
	ds_read_b128 v[204:207], v194 offset:55296
	ds_read_b128 v[208:211], v194 offset:56320
	global_load_lds_dwordx4 v[212:213], off
	s_add_i32 m0, s48, 0x2000
	s_add_u32 s42, s42, 0x80080
	v_lshl_add_u64 v[212:213], v[214:215], 0, s[22:23]
	s_addc_u32 s43, s43, 0
	s_add_i32 s48, s59, s66
	global_load_lds_dwordx4 v[212:213], off
	v_lshl_add_u64 v[212:213], s[42:43], 0, v[164:165]
	s_mov_b32 m0, s48
	s_nop 0
	global_load_lds_dwordx4 v[212:213], off
	v_lshl_add_u64 v[212:213], s[42:43], 0, v[168:169]
	s_add_i32 m0, s48, 0x2000
	s_nop 0
	global_load_lds_dwordx4 v[212:213], off
	v_lshl_add_u64 v[212:213], v[216:217], 0, s[22:23]
	s_mov_b32 m0, s76
	s_nop 0
	global_load_lds_dwordx4 v[212:213], off
	v_lshl_add_u64 v[212:213], v[218:219], 0, s[22:23]
	s_mov_b32 m0, s77
	s_nop 0
	global_load_lds_dwordx4 v[212:213], off
	s_waitcnt vmcnt(8)
	s_waitcnt lgkmcnt(0)
	s_barrier
	s_setprio 1
	s_waitcnt lgkmcnt(0)
	v_mfma_f32_16x16x32_bf16 v[62:65], v[82:85], v[174:177], v[62:65]
	v_mfma_f32_16x16x32_bf16 v[58:61], v[98:101], v[174:177], v[58:61]
	v_mfma_f32_16x16x32_bf16 v[46:49], v[82:85], v[182:185], v[46:49]
	v_mfma_f32_16x16x32_bf16 v[42:45], v[98:101], v[182:185], v[42:45]
	v_mfma_f32_16x16x32_bf16 v[30:33], v[82:85], v[196:199], v[30:33]
	v_mfma_f32_16x16x32_bf16 v[26:29], v[98:101], v[196:199], v[26:29]
	v_mfma_f32_16x16x32_bf16 v[14:17], v[82:85], v[204:207], v[14:17]
	v_mfma_f32_16x16x32_bf16 v[10:13], v[98:101], v[204:207], v[10:13]
	v_mfma_f32_16x16x32_bf16 v[62:65], v[90:93], v[178:181], v[62:65]
	v_mfma_f32_16x16x32_bf16 v[58:61], v[102:105], v[178:181], v[58:61]
	v_mfma_f32_16x16x32_bf16 v[46:49], v[90:93], v[186:189], v[46:49]
	v_mfma_f32_16x16x32_bf16 v[42:45], v[102:105], v[186:189], v[42:45]
	v_mfma_f32_16x16x32_bf16 v[30:33], v[90:93], v[200:203], v[30:33]
	v_mfma_f32_16x16x32_bf16 v[26:29], v[102:105], v[200:203], v[26:29]
	v_mfma_f32_16x16x32_bf16 v[14:17], v[90:93], v[208:211], v[14:17]
	v_mfma_f32_16x16x32_bf16 v[10:13], v[102:105], v[208:211], v[10:13]
	s_setprio 0
	s_setprio 1
	v_mfma_f32_16x16x32_bf16 v[54:57], v[146:149], v[174:177], v[54:57]
	v_mfma_f32_16x16x32_bf16 v[50:53], v[154:157], v[174:177], v[50:53]
	v_mfma_f32_16x16x32_bf16 v[38:41], v[146:149], v[182:185], v[38:41]
	v_mfma_f32_16x16x32_bf16 v[34:37], v[154:157], v[182:185], v[34:37]
	v_mfma_f32_16x16x32_bf16 v[22:25], v[146:149], v[196:199], v[22:25]
	v_mfma_f32_16x16x32_bf16 v[18:21], v[154:157], v[196:199], v[18:21]
	v_mfma_f32_16x16x32_bf16 v[6:9], v[146:149], v[204:207], v[6:9]
	v_mfma_f32_16x16x32_bf16 v[2:5], v[154:157], v[204:207], v[2:5]
	v_mfma_f32_16x16x32_bf16 v[54:57], v[150:153], v[178:181], v[54:57]
	v_mfma_f32_16x16x32_bf16 v[50:53], v[158:161], v[178:181], v[50:53]
	v_mfma_f32_16x16x32_bf16 v[38:41], v[150:153], v[186:189], v[38:41]
	v_mfma_f32_16x16x32_bf16 v[34:37], v[158:161], v[186:189], v[34:37]
	v_mfma_f32_16x16x32_bf16 v[22:25], v[150:153], v[200:203], v[22:25]
	v_mfma_f32_16x16x32_bf16 v[18:21], v[158:161], v[200:203], v[18:21]
	v_mfma_f32_16x16x32_bf16 v[6:9], v[150:153], v[208:211], v[6:9]
	v_mfma_f32_16x16x32_bf16 v[2:5], v[158:161], v[208:211], v[2:5]
	s_setprio 0
	s_add_i32 s39, s39, 2
	s_add_u32 s40, s40, 0x100
	s_addc_u32 s41, s41, 0
	s_add_u32 s29, s29, 0x100
	s_addc_u32 s31, s31, 0
	s_cmp_gt_u32 s39, 29
	s_barrier
	s_cbranch_scc0 .LBB0_362
	s_and_b64 vcc, exec, s[24:25]
	s_cbranch_vccz .LBB0_365
	s_barrier

; #define PG8_STAGE(bufoff, gbase, voff) do { _Pragma("unroll") for (int _i = 0; _i < 2; ++_i) \
;         __builtin_amdgcn_global_load_lds((const unsigned*)((const char*)(gbase) + (voff)[_i]), (LAS unsigned*)(lds + (bufoff) + ldsw + _i * 8192), 16, 0, 0); } while (0)
; #define PG8_LDA(dst, b, h) do { _Pragma("unroll") for (int m = 0; m < 4; ++m) _Pragma("unroll") for (int k = 0; k < 2; ++k) dst[m][k] = *(const LAS bf16x8*)(lds + PG8_SA(b, h) + aoff + m * 2048 + k * 1024); } while (0)
; #define PG8_LDB(dst, b, h) do { _Pragma("unroll") for (int n = 0; n < 2; ++n) _Pragma("unroll") for (int k = 0; k < 2; ++k) dst[n][k] = *(const LAS bf16x8*)(lds + PG8_SB(b, h) + boff + n * 2048 + k * 1024); } while (0)
; #define PG8_MMA(ai, bj, At, Bt) do { __builtin_amdgcn_s_setprio(1); _Pragma("unroll") for (int m = 0; m < 4; ++m) _Pragma("unroll") for (int n = 0; n < 2; ++n) _Pragma("unroll") for (int k = 0; k < 2; ++k) \
;         acc[ai][bj][m][n] = __builtin_amdgcn_mfma_f32_16x16x32_bf16(Bt[n][k], At[m][k], acc[ai][bj][m][n], 0, 0, 0); __builtin_amdgcn_s_setprio(0); } while (0)
; #define PG8_WAIT_V(n) asm volatile("s_waitcnt vmcnt(" #n ")" ::: "memory")
; #define PG8_WAIT_L(n) asm volatile("s_waitcnt lgkmcnt(" #n ")" ::: "memory")
; #define PG8_BAR __builtin_amdgcn_s_barrier()
; #define PG8_SCHED __builtin_amdgcn_sched_barrier(0)
; template <class Epi, bool ALIGN_EPI, bool SP2>
; __device__ __forceinline__ void gemm_phase(LAS unsigned char* lds, const Sched2& S, const Epi& E) {
;     ...
;         for (int t = 0; t < nt; t += 2) {
;             const bool last = (t == nt - 2);
;             const char* a1 = cA + (size_t)(t + 1) * kstep;
;             const char* a2 = last ? nA : cA + (size_t)(t + 2) * kstep; const char* b2 = last ? nB : cB + (size_t)(t + 2) * kstep;
;             const char* a3 = a2 + kstep; const char* b3 = b2 + kstep;
;             if constexpr (SP2) {
;             PG8_LDB(B0, 0, 0); PG8_LDB(B1, 0, 1); PG8_SCHED; PG8_LDA(At, 0, 0); PG8_STAGE(PG8_SA(1, 1), a1 + hstep, voffA);
;             PG8_WAIT_V(8); PG8_WAIT_L(0); PG8_BAR; PG8_MMA(0, 0, At, B0); PG8_MMA(0, 1, At, B1); PG8_BAR; PG8_SCHED;
;             PG8_LDA(At, 0, 1); PG8_STAGE(PG8_SB(0, 0), b2, voffB); PG8_STAGE(PG8_SB(0, 1), b2 + hstep, voffB); PG8_STAGE(PG8_SA(0, 0), a2, voffA);
;             PG8_WAIT_V(8); PG8_WAIT_L(0); PG8_BAR; PG8_MMA(1, 0, At, B0); PG8_MMA(1, 1, At, B1); PG8_BAR; PG8_SCHED;
.LBB0_471:
	ds_read_b128 v[130:133], v213
	ds_read_b128 v[134:137], v213 offset:1024
	ds_read_b128 v[138:141], v213 offset:2048
	ds_read_b128 v[142:145], v213 offset:3072
	ds_read_b128 v[146:149], v217
	ds_read_b128 v[150:153], v217 offset:1024
	ds_read_b128 v[154:157], v217 offset:2048
	ds_read_b128 v[158:161], v217 offset:3072
	s_add_u32 s38, s36, 0xfffc0080
	s_addc_u32 s39, s37, -1
	s_cmp_eq_u32 s35, 12
	s_cselect_b32 s41, s27, s39
	s_cselect_b32 s40, s26, s38
	s_cselect_b32 s39, s29, s25
	s_cselect_b32 s38, s28, s23
	v_lshl_add_u64 v[202:203], s[36:37], 0, v[174:175]
	s_add_i32 m0, s31, 0xc000
	ds_read_b128 v[178:181], v238
	ds_read_b128 v[182:185], v238 offset:1024
	ds_read_b128 v[186:189], v238 offset:2048
	ds_read_b128 v[190:193], v238 offset:3072
	ds_read_b128 v[218:221], v238 offset:4096
	ds_read_b128 v[222:225], v238 offset:5120
	ds_read_b128 v[226:229], v238 offset:6144
	ds_read_b128 v[230:233], v238 offset:7168
	global_load_lds_dwordx4 v[202:203], off
	v_lshl_add_u64 v[202:203], s[36:37], 0, v[176:177]
	s_add_i32 m0, s31, 0xe000
	s_nop 0
	global_load_lds_dwordx4 v[202:203], off
	s_waitcnt vmcnt(8)
	s_waitcnt lgkmcnt(0)
	s_barrier
	s_setprio 1
	s_waitcnt lgkmcnt(0)
	v_mfma_f32_16x16x32_bf16 v[126:129], v[130:133], v[178:181], v[126:129]
	v_mfma_f32_16x16x32_bf16 v[122:125], v[138:141], v[178:181], v[122:125]
	v_mfma_f32_16x16x32_bf16 v[110:113], v[130:133], v[186:189], v[110:113]
	v_mfma_f32_16x16x32_bf16 v[106:109], v[138:141], v[186:189], v[106:109]
	v_mfma_f32_16x16x32_bf16 v[94:97], v[130:133], v[218:221], v[94:97]
	v_mfma_f32_16x16x32_bf16 v[90:93], v[138:141], v[218:221], v[90:93]
	v_mfma_f32_16x16x32_bf16 v[78:81], v[130:133], v[226:229], v[78:81]
	v_mfma_f32_16x16x32_bf16 v[74:77], v[138:141], v[226:229], v[74:77]
	v_mfma_f32_16x16x32_bf16 v[126:129], v[134:137], v[182:185], v[126:129]
	v_mfma_f32_16x16x32_bf16 v[122:125], v[142:145], v[182:185], v[122:125]
	v_mfma_f32_16x16x32_bf16 v[110:113], v[134:137], v[190:193], v[110:113]
	v_mfma_f32_16x16x32_bf16 v[106:109], v[142:145], v[190:193], v[106:109]
	v_mfma_f32_16x16x32_bf16 v[94:97], v[134:137], v[222:225], v[94:97]
	v_mfma_f32_16x16x32_bf16 v[90:93], v[142:145], v[222:225], v[90:93]
	v_mfma_f32_16x16x32_bf16 v[78:81], v[134:137], v[230:233], v[78:81]
	v_mfma_f32_16x16x32_bf16 v[74:77], v[142:145], v[230:233], v[74:77]
	s_setprio 0
	s_setprio 1
	v_mfma_f32_16x16x32_bf16 v[118:121], v[146:149], v[178:181], v[118:121]
	v_mfma_f32_16x16x32_bf16 v[114:117], v[154:157], v[178:181], v[114:117]
	v_mfma_f32_16x16x32_bf16 v[102:105], v[146:149], v[186:189], v[102:105]
	v_mfma_f32_16x16x32_bf16 v[98:101], v[154:157], v[186:189], v[98:101]
	v_mfma_f32_16x16x32_bf16 v[86:89], v[146:149], v[218:221], v[86:89]
	v_mfma_f32_16x16x32_bf16 v[82:85], v[154:157], v[218:221], v[82:85]
	v_mfma_f32_16x16x32_bf16 v[70:73], v[146:149], v[226:229], v[70:73]
	v_mfma_f32_16x16x32_bf16 v[66:69], v[154:157], v[226:229], v[66:69]
	v_mfma_f32_16x16x32_bf16 v[118:121], v[150:153], v[182:185], v[118:121]
	v_mfma_f32_16x16x32_bf16 v[114:117], v[158:161], v[182:185], v[114:117]
	v_mfma_f32_16x16x32_bf16 v[102:105], v[150:153], v[190:193], v[102:105]
	v_mfma_f32_16x16x32_bf16 v[98:101], v[158:161], v[190:193], v[98:101]
	v_mfma_f32_16x16x32_bf16 v[86:89], v[150:153], v[222:225], v[86:89]
	v_mfma_f32_16x16x32_bf16 v[82:85], v[158:161], v[222:225], v[82:85]
	v_mfma_f32_16x16x32_bf16 v[70:73], v[150:153], v[230:233], v[70:73]
	v_mfma_f32_16x16x32_bf16 v[66:69], v[158:161], v[230:233], v[66:69]
	s_setprio 0
	s_barrier
	s_add_i32 s58, s76, s48
	v_lshl_add_u64 v[202:203], s[38:39], 0, v[164:165]
	s_mov_b32 m0, s58
	ds_read_b128 v[178:181], v238 offset:16384
	ds_read_b128 v[182:185], v238 offset:17408
	ds_read_b128 v[186:189], v238 offset:18432
	ds_read_b128 v[190:193], v238 offset:19456
	ds_read_b128 v[218:221], v238 offset:20480
	ds_read_b128 v[222:225], v238 offset:21504
	ds_read_b128 v[226:229], v238 offset:22528
	ds_read_b128 v[230:233], v238 offset:23552
	global_load_lds_dwordx4 v[202:203], off
	s_add_i32 m0, s58, 0x2000
	s_add_u32 s58, s38, 0x40000
	v_lshl_add_u64 v[206:207], s[38:39], 0, v[168:169]
	s_addc_u32 s59, s39, 0
	s_add_i32 s81, s77, s48
	global_load_lds_dwordx4 v[206:207], off
	v_lshl_add_u64 v[210:211], s[58:59], 0, v[164:165]
	s_mov_b32 m0, s81
	v_lshl_add_u64 v[214:215], s[40:41], 0, v[166:167]
	global_load_lds_dwordx4 v[210:211], off
	v_lshl_add_u64 v[210:211], s[58:59], 0, v[168:169]
	s_add_i32 m0, s81, 0x2000
	s_nop 0
	global_load_lds_dwordx4 v[210:211], off
	v_lshl_add_u64 v[210:211], s[40:41], 0, v[162:163]
	s_mov_b32 m0, s31
	s_nop 0
	global_load_lds_dwordx4 v[210:211], off
	s_mov_b32 m0, s49
	s_nop 0
	global_load_lds_dwordx4 v[214:215], off
	s_waitcnt vmcnt(8)
	s_waitcnt lgkmcnt(0)
	s_barrier
; #define PG8_STAGE(bufoff, gbase, voff) do { _Pragma("unroll") for (int _i = 0; _i < 2; ++_i) \
;         __builtin_amdgcn_global_load_lds((const unsigned*)((const char*)(gbase) + (voff)[_i]), (LAS unsigned*)(lds + (bufoff) + ldsw + _i * 8192), 16, 0, 0); } while (0)
; #define PG8_LDA(dst, b, h) do { _Pragma("unroll") for (int m = 0; m < 4; ++m) _Pragma("unroll") for (int k = 0; k < 2; ++k) dst[m][k] = *(const LAS bf16x8*)(lds + PG8_SA(b, h) + aoff + m * 2048 + k * 1024); } while (0)
; #define PG8_LDB(dst, b, h) do { _Pragma("unroll") for (int n = 0; n < 2; ++n) _Pragma("unroll") for (int k = 0; k < 2; ++k) dst[n][k] = *(const LAS bf16x8*)(lds + PG8_SB(b, h) + boff + n * 2048 + k * 1024); } while (0)
; #define PG8_MMA(ai, bj, At, Bt) do { __builtin_amdgcn_s_setprio(1); _Pragma("unroll") for (int m = 0; m < 4; ++m) _Pragma("unroll") for (int n = 0; n < 2; ++n) _Pragma("unroll") for (int k = 0; k < 2; ++k) \
;         acc[ai][bj][m][n] = __builtin_amdgcn_mfma_f32_16x16x32_bf16(Bt[n][k], At[m][k], acc[ai][bj][m][n], 0, 0, 0); __builtin_amdgcn_s_setprio(0); } while (0)
; #define PG8_WAIT_V(n) asm volatile("s_waitcnt vmcnt(" #n ")" ::: "memory")
; #define PG8_WAIT_L(n) asm volatile("s_waitcnt lgkmcnt(" #n ")" ::: "memory")
; #define PG8_BAR __builtin_amdgcn_s_barrier()
; #define PG8_SCHED __builtin_amdgcn_sched_barrier(0)
; template <class Epi, bool ALIGN_EPI, bool SP2>
; __device__ __forceinline__ void gemm_phase(LAS unsigned char* lds, const Sched2& S, const Epi& E) {
;     ...
;             PG8_WAIT_V(8); PG8_WAIT_L(0); PG8_BAR; PG8_MMA(0, 0, At, B0); PG8_MMA(0, 1, At, B1); PG8_BAR; PG8_SCHED;
;             PG8_LDA(At, 0, 1); PG8_STAGE(PG8_SB(0, 0), b2, voffB); PG8_STAGE(PG8_SB(0, 1), b2 + hstep, voffB); PG8_STAGE(PG8_SA(0, 0), a2, voffA);
;             PG8_WAIT_V(8); PG8_WAIT_L(0); PG8_BAR; PG8_MMA(1, 0, At, B0); PG8_MMA(1, 1, At, B1); PG8_BAR; PG8_SCHED;
;             PG8_LDB(B0, 1, 0); PG8_LDB(B1, 1, 1); PG8_SCHED; PG8_LDA(At, 1, 0); PG8_STAGE(PG8_SA(0, 1), a2 + hstep, voffA);
;             PG8_WAIT_V(8); PG8_WAIT_L(0); PG8_BAR; PG8_MMA(0, 0, At, B0); PG8_MMA(0, 1, At, B1); PG8_BAR; PG8_SCHED;
	s_setprio 1
	s_waitcnt lgkmcnt(0)
	v_mfma_f32_16x16x32_bf16 v[62:65], v[130:133], v[178:181], v[62:65]
	v_mfma_f32_16x16x32_bf16 v[58:61], v[138:141], v[178:181], v[58:61]
	v_mfma_f32_16x16x32_bf16 v[46:49], v[130:133], v[186:189], v[46:49]
	v_mfma_f32_16x16x32_bf16 v[42:45], v[138:141], v[186:189], v[42:45]
	v_mfma_f32_16x16x32_bf16 v[30:33], v[130:133], v[218:221], v[30:33]
	v_mfma_f32_16x16x32_bf16 v[26:29], v[138:141], v[218:221], v[26:29]
	v_mfma_f32_16x16x32_bf16 v[22:25], v[130:133], v[226:229], v[22:25]
	v_mfma_f32_16x16x32_bf16 v[10:13], v[138:141], v[226:229], v[10:13]
	v_mfma_f32_16x16x32_bf16 v[62:65], v[134:137], v[182:185], v[62:65]
	v_mfma_f32_16x16x32_bf16 v[58:61], v[142:145], v[182:185], v[58:61]
	v_mfma_f32_16x16x32_bf16 v[46:49], v[134:137], v[190:193], v[46:49]
	v_mfma_f32_16x16x32_bf16 v[42:45], v[142:145], v[190:193], v[42:45]
	v_mfma_f32_16x16x32_bf16 v[30:33], v[134:137], v[222:225], v[30:33]
	v_mfma_f32_16x16x32_bf16 v[26:29], v[142:145], v[222:225], v[26:29]
	v_mfma_f32_16x16x32_bf16 v[22:25], v[134:137], v[230:233], v[22:25]
	v_mfma_f32_16x16x32_bf16 v[10:13], v[142:145], v[230:233], v[10:13]
	s_setprio 0
	s_setprio 1
	v_mfma_f32_16x16x32_bf16 v[54:57], v[146:149], v[178:181], v[54:57]
	v_mfma_f32_16x16x32_bf16 v[50:53], v[154:157], v[178:181], v[50:53]
	v_mfma_f32_16x16x32_bf16 v[38:41], v[146:149], v[186:189], v[38:41]
	v_mfma_f32_16x16x32_bf16 v[34:37], v[154:157], v[186:189], v[34:37]
	v_mfma_f32_16x16x32_bf16 v[18:21], v[146:149], v[218:221], v[18:21]
	v_mfma_f32_16x16x32_bf16 v[14:17], v[154:157], v[218:221], v[14:17]
	v_mfma_f32_16x16x32_bf16 v[6:9], v[146:149], v[226:229], v[6:9]
	v_mfma_f32_16x16x32_bf16 v[2:5], v[154:157], v[226:229], v[2:5]
	v_mfma_f32_16x16x32_bf16 v[54:57], v[150:153], v[182:185], v[54:57]
	v_mfma_f32_16x16x32_bf16 v[50:53], v[158:161], v[182:185], v[50:53]
	v_mfma_f32_16x16x32_bf16 v[38:41], v[150:153], v[190:193], v[38:41]
	v_mfma_f32_16x16x32_bf16 v[34:37], v[158:161], v[190:193], v[34:37]
	v_mfma_f32_16x16x32_bf16 v[18:21], v[150:153], v[222:225], v[18:21]
	v_mfma_f32_16x16x32_bf16 v[14:17], v[158:161], v[222:225], v[14:17]
	v_mfma_f32_16x16x32_bf16 v[6:9], v[150:153], v[230:233], v[6:9]
	v_mfma_f32_16x16x32_bf16 v[2:5], v[158:161], v[230:233], v[2:5]
	s_setprio 0
	s_barrier
	s_add_i32 s58, 0, 0x18000
	s_add_i32 s59, 0, 0x1c000
	v_add_u32_e32 v142, s58, v195
	v_add_u32_e32 v158, s59, v195
	ds_read_b128 v[130:133], v142
	ds_read_b128 v[134:137], v142 offset:1024
	ds_read_b128 v[138:141], v142 offset:2048
	ds_read_b128 v[142:145], v142 offset:3072
	ds_read_b128 v[146:149], v158
	ds_read_b128 v[150:153], v158 offset:1024
	ds_read_b128 v[154:157], v158 offset:2048
	ds_read_b128 v[158:161], v158 offset:3072
	s_add_u32 s40, s40, 0x40000
	s_addc_u32 s41, s41, 0
	s_mov_b32 m0, s70
	v_lshl_add_u64 v[234:235], s[40:41], 0, v[162:163]
	ds_read_b128 v[178:181], v238 offset:32768
	ds_read_b128 v[182:185], v238 offset:33792
	ds_read_b128 v[186:189], v238 offset:34816
	ds_read_b128 v[190:193], v238 offset:35840
	ds_read_b128 v[218:221], v238 offset:36864
	ds_read_b128 v[222:225], v238 offset:37888
	ds_read_b128 v[226:229], v238 offset:38912
	ds_read_b128 v[230:233], v238 offset:39936
	global_load_lds_dwordx4 v[234:235], off
	v_lshl_add_u64 v[234:235], s[40:41], 0, v[166:167]
	s_mov_b32 m0, s71
	s_nop 0
	global_load_lds_dwordx4 v[234:235], off
	s_waitcnt vmcnt(8)
	s_waitcnt lgkmcnt(0)
	s_barrier
	s_setprio 1
	s_waitcnt lgkmcnt(0)
	v_mfma_f32_16x16x32_bf16 v[126:129], v[130:133], v[178:181], v[126:129]
	v_mfma_f32_16x16x32_bf16 v[122:125], v[138:141], v[178:181], v[122:125]
	v_mfma_f32_16x16x32_bf16 v[110:113], v[130:133], v[186:189], v[110:113]
	v_mfma_f32_16x16x32_bf16 v[106:109], v[138:141], v[186:189], v[106:109]
	v_mfma_f32_16x16x32_bf16 v[94:97], v[130:133], v[218:221], v[94:97]
	v_mfma_f32_16x16x32_bf16 v[90:93], v[138:141], v[218:221], v[90:93]
	v_mfma_f32_16x16x32_bf16 v[78:81], v[130:133], v[226:229], v[78:81]
	v_mfma_f32_16x16x32_bf16 v[74:77], v[138:141], v[226:229], v[74:77]
	v_mfma_f32_16x16x32_bf16 v[126:129], v[134:137], v[182:185], v[126:129]
	v_mfma_f32_16x16x32_bf16 v[122:125], v[142:145], v[182:185], v[122:125]
	v_mfma_f32_16x16x32_bf16 v[110:113], v[134:137], v[190:193], v[110:113]
	v_mfma_f32_16x16x32_bf16 v[106:109], v[142:145], v[190:193], v[106:109]
	v_mfma_f32_16x16x32_bf16 v[94:97], v[134:137], v[222:225], v[94:97]
	v_mfma_f32_16x16x32_bf16 v[90:93], v[142:145], v[222:225], v[90:93]
	v_mfma_f32_16x16x32_bf16 v[78:81], v[134:137], v[230:233], v[78:81]
	v_mfma_f32_16x16x32_bf16 v[74:77], v[142:145], v[230:233], v[74:77]
	s_setprio 0
	s_setprio 1
	v_mfma_f32_16x16x32_bf16 v[118:121], v[146:149], v[178:181], v[118:121]
	v_mfma_f32_16x16x32_bf16 v[114:117], v[154:157], v[178:181], v[114:117]
	v_mfma_f32_16x16x32_bf16 v[102:105], v[146:149], v[186:189], v[102:105]
	v_mfma_f32_16x16x32_bf16 v[98:101], v[154:157], v[186:189], v[98:101]
	v_mfma_f32_16x16x32_bf16 v[86:89], v[146:149], v[218:221], v[86:89]
	v_mfma_f32_16x16x32_bf16 v[82:85], v[154:157], v[218:221], v[82:85]
	v_mfma_f32_16x16x32_bf16 v[70:73], v[146:149], v[226:229], v[70:73]
	v_mfma_f32_16x16x32_bf16 v[66:69], v[154:157], v[226:229], v[66:69]
	v_mfma_f32_16x16x32_bf16 v[118:121], v[150:153], v[182:185], v[118:121]
	v_mfma_f32_16x16x32_bf16 v[114:117], v[158:161], v[182:185], v[114:117]
	v_mfma_f32_16x16x32_bf16 v[102:105], v[150:153], v[190:193], v[102:105]
	v_mfma_f32_16x16x32_bf16 v[98:101], v[158:161], v[190:193], v[98:101]
	v_mfma_f32_16x16x32_bf16 v[86:89], v[150:153], v[222:225], v[86:89]
	v_mfma_f32_16x16x32_bf16 v[82:85], v[158:161], v[222:225], v[82:85]
	v_mfma_f32_16x16x32_bf16 v[70:73], v[150:153], v[230:233], v[70:73]
	v_mfma_f32_16x16x32_bf16 v[66:69], v[158:161], v[230:233], v[66:69]
	s_setprio 0
	s_barrier
; #define PG8_STAGE(bufoff, gbase, voff) do { _Pragma("unroll") for (int _i = 0; _i < 2; ++_i) \
;         __builtin_amdgcn_global_load_lds((const unsigned*)((const char*)(gbase) + (voff)[_i]), (LAS unsigned*)(lds + (bufoff) + ldsw + _i * 8192), 16, 0, 0); } while (0)
; #define PG8_LDA(dst, b, h) do { _Pragma("unroll") for (int m = 0; m < 4; ++m) _Pragma("unroll") for (int k = 0; k < 2; ++k) dst[m][k] = *(const LAS bf16x8*)(lds + PG8_SA(b, h) + aoff + m * 2048 + k * 1024); } while (0)
; #define PG8_LDB(dst, b, h) do { _Pragma("unroll") for (int n = 0; n < 2; ++n) _Pragma("unroll") for (int k = 0; k < 2; ++k) dst[n][k] = *(const LAS bf16x8*)(lds + PG8_SB(b, h) + boff + n * 2048 + k * 1024); } while (0)
; #define PG8_MMA(ai, bj, At, Bt) do { __builtin_amdgcn_s_setprio(1); _Pragma("unroll") for (int m = 0; m < 4; ++m) _Pragma("unroll") for (int n = 0; n < 2; ++n) _Pragma("unroll") for (int k = 0; k < 2; ++k) \
;         acc[ai][bj][m][n] = __builtin_amdgcn_mfma_f32_16x16x32_bf16(Bt[n][k], At[m][k], acc[ai][bj][m][n], 0, 0, 0); __builtin_amdgcn_s_setprio(0); } while (0)
; #define PG8_WAIT_V(n) asm volatile("s_waitcnt vmcnt(" #n ")" ::: "memory")
; #define PG8_WAIT_L(n) asm volatile("s_waitcnt lgkmcnt(" #n ")" ::: "memory")
; #define PG8_BAR __builtin_amdgcn_s_barrier()
; #define PG8_SCHED __builtin_amdgcn_sched_barrier(0)
; template <class Epi, bool ALIGN_EPI, bool SP2>
; __device__ __forceinline__ void gemm_phase(LAS unsigned char* lds, const Sched2& S, const Epi& E) {
;     ...
;         for (int t = 0; t < nt; t += 2) {
;     ...
;             PG8_LDB(B0, 1, 0); PG8_LDB(B1, 1, 1); PG8_SCHED; PG8_LDA(At, 1, 0); PG8_STAGE(PG8_SA(0, 1), a2 + hstep, voffA);
;             PG8_WAIT_V(8); PG8_WAIT_L(0); PG8_BAR; PG8_MMA(0, 0, At, B0); PG8_MMA(0, 1, At, B1); PG8_BAR; PG8_SCHED;
;             PG8_LDA(At, 1, 1); PG8_STAGE(PG8_SB(1, 0), b3, voffB); PG8_STAGE(PG8_SB(1, 1), b3 + hstep, voffB); PG8_STAGE(PG8_SA(1, 0), a3, voffA);
;             PG8_WAIT_V(8); PG8_WAIT_L(0); PG8_BAR; PG8_MMA(1, 0, At, B0); PG8_MMA(1, 1, At, B1); PG8_BAR; PG8_SCHED;
	s_add_i32 s40, s58, s48
	v_lshl_add_u64 v[202:203], v[202:203], 0, s[16:17]
	s_mov_b32 m0, s40
	ds_read_b128 v[178:181], v238 offset:49152
	ds_read_b128 v[182:185], v238 offset:50176
	ds_read_b128 v[186:189], v238 offset:51200
	ds_read_b128 v[190:193], v238 offset:52224
	ds_read_b128 v[218:221], v238 offset:53248
	ds_read_b128 v[222:225], v238 offset:54272
	ds_read_b128 v[226:229], v238 offset:55296
	ds_read_b128 v[230:233], v238 offset:56320
	global_load_lds_dwordx4 v[202:203], off
	s_add_i32 m0, s40, 0x2000
	s_add_u32 s38, s38, 0x40080
	v_lshl_add_u64 v[202:203], v[206:207], 0, s[16:17]
	s_addc_u32 s39, s39, 0
	s_add_i32 s40, s59, s48
	global_load_lds_dwordx4 v[202:203], off
	v_lshl_add_u64 v[202:203], s[38:39], 0, v[164:165]
	s_mov_b32 m0, s40
	s_nop 0
	global_load_lds_dwordx4 v[202:203], off
	v_lshl_add_u64 v[202:203], s[38:39], 0, v[168:169]
	s_add_i32 m0, s40, 0x2000
	s_nop 0
	global_load_lds_dwordx4 v[202:203], off
	v_lshl_add_u64 v[202:203], v[210:211], 0, s[16:17]
	s_mov_b32 m0, s73
	s_nop 0
	global_load_lds_dwordx4 v[202:203], off
	v_lshl_add_u64 v[202:203], v[214:215], 0, s[16:17]
	s_mov_b32 m0, s74
	s_nop 0
	global_load_lds_dwordx4 v[202:203], off
	s_waitcnt vmcnt(8)
	s_waitcnt lgkmcnt(0)
	s_barrier
	s_setprio 1
	s_waitcnt lgkmcnt(0)
	v_mfma_f32_16x16x32_bf16 v[62:65], v[130:133], v[178:181], v[62:65]
	v_mfma_f32_16x16x32_bf16 v[58:61], v[138:141], v[178:181], v[58:61]
	v_mfma_f32_16x16x32_bf16 v[46:49], v[130:133], v[186:189], v[46:49]
	v_mfma_f32_16x16x32_bf16 v[42:45], v[138:141], v[186:189], v[42:45]
	v_mfma_f32_16x16x32_bf16 v[30:33], v[130:133], v[218:221], v[30:33]
	v_mfma_f32_16x16x32_bf16 v[26:29], v[138:141], v[218:221], v[26:29]
	v_mfma_f32_16x16x32_bf16 v[22:25], v[130:133], v[226:229], v[22:25]
	v_mfma_f32_16x16x32_bf16 v[10:13], v[138:141], v[226:229], v[10:13]
	v_mfma_f32_16x16x32_bf16 v[62:65], v[134:137], v[182:185], v[62:65]
	v_mfma_f32_16x16x32_bf16 v[58:61], v[142:145], v[182:185], v[58:61]
	v_mfma_f32_16x16x32_bf16 v[46:49], v[134:137], v[190:193], v[46:49]
	v_mfma_f32_16x16x32_bf16 v[42:45], v[142:145], v[190:193], v[42:45]
	v_mfma_f32_16x16x32_bf16 v[30:33], v[134:137], v[222:225], v[30:33]
	v_mfma_f32_16x16x32_bf16 v[26:29], v[142:145], v[222:225], v[26:29]
	v_mfma_f32_16x16x32_bf16 v[22:25], v[134:137], v[230:233], v[22:25]
	v_mfma_f32_16x16x32_bf16 v[10:13], v[142:145], v[230:233], v[10:13]
	s_setprio 0
	s_setprio 1
	v_mfma_f32_16x16x32_bf16 v[54:57], v[146:149], v[178:181], v[54:57]
	v_mfma_f32_16x16x32_bf16 v[50:53], v[154:157], v[178:181], v[50:53]
	v_mfma_f32_16x16x32_bf16 v[38:41], v[146:149], v[186:189], v[38:41]
	v_mfma_f32_16x16x32_bf16 v[34:37], v[154:157], v[186:189], v[34:37]
	v_mfma_f32_16x16x32_bf16 v[18:21], v[146:149], v[218:221], v[18:21]
	v_mfma_f32_16x16x32_bf16 v[14:17], v[154:157], v[218:221], v[14:17]
	v_mfma_f32_16x16x32_bf16 v[6:9], v[146:149], v[226:229], v[6:9]
	v_mfma_f32_16x16x32_bf16 v[2:5], v[154:157], v[226:229], v[2:5]
	v_mfma_f32_16x16x32_bf16 v[54:57], v[150:153], v[182:185], v[54:57]
	v_mfma_f32_16x16x32_bf16 v[50:53], v[158:161], v[182:185], v[50:53]
	v_mfma_f32_16x16x32_bf16 v[38:41], v[150:153], v[190:193], v[38:41]
	v_mfma_f32_16x16x32_bf16 v[34:37], v[158:161], v[190:193], v[34:37]
	v_mfma_f32_16x16x32_bf16 v[18:21], v[150:153], v[222:225], v[18:21]
	v_mfma_f32_16x16x32_bf16 v[14:17], v[158:161], v[222:225], v[14:17]
	v_mfma_f32_16x16x32_bf16 v[6:9], v[150:153], v[230:233], v[6:9]
	v_mfma_f32_16x16x32_bf16 v[2:5], v[158:161], v[230:233], v[2:5]
	s_setprio 0
	s_add_i32 s35, s35, 2
	s_add_u32 s36, s36, 0x100
	s_addc_u32 s37, s37, 0
	s_add_u32 s23, s23, 0x100
	s_addc_u32 s25, s25, 0
	s_cmp_gt_u32 s35, 13
	s_barrier
	s_cbranch_scc0 .LBB0_471
	s_and_b64 vcc, exec, s[18:19]
	s_cbranch_vccz .LBB0_474
	s_barrier

; #define PG8_STAGE(bufoff, gbase, voff) do { _Pragma("unroll") for (int _i = 0; _i < 2; ++_i) \
;         __builtin_amdgcn_global_load_lds((const unsigned*)((const char*)(gbase) + (voff)[_i]), (LAS unsigned*)(lds + (bufoff) + ldsw + _i * 8192), 16, 0, 0); } while (0)
; #define PG8_LDA(dst, b, h) do { _Pragma("unroll") for (int m = 0; m < 4; ++m) _Pragma("unroll") for (int k = 0; k < 2; ++k) dst[m][k] = *(const LAS bf16x8*)(lds + PG8_SA(b, h) + aoff + m * 2048 + k * 1024); } while (0)
; #define PG8_LDB(dst, b, h) do { _Pragma("unroll") for (int n = 0; n < 2; ++n) _Pragma("unroll") for (int k = 0; k < 2; ++k) dst[n][k] = *(const LAS bf16x8*)(lds + PG8_SB(b, h) + boff + n * 2048 + k * 1024); } while (0)
; #define PG8_MMA(ai, bj, At, Bt) do { __builtin_amdgcn_s_setprio(1); _Pragma("unroll") for (int m = 0; m < 4; ++m) _Pragma("unroll") for (int n = 0; n < 2; ++n) _Pragma("unroll") for (int k = 0; k < 2; ++k) \
;         acc[ai][bj][m][n] = __builtin_amdgcn_mfma_f32_16x16x32_bf16(Bt[n][k], At[m][k], acc[ai][bj][m][n], 0, 0, 0); __builtin_amdgcn_s_setprio(0); } while (0)
; #define PG8_WAIT_V(n) asm volatile("s_waitcnt vmcnt(" #n ")" ::: "memory")
; #define PG8_WAIT_L(n) asm volatile("s_waitcnt lgkmcnt(" #n ")" ::: "memory")
; #define PG8_BAR __builtin_amdgcn_s_barrier()
; #define PG8_SCHED __builtin_amdgcn_sched_barrier(0)
; template <class Epi, bool ALIGN_EPI, bool SP2>
; __device__ __forceinline__ void gemm_phase(LAS unsigned char* lds, const Sched2& S, const Epi& E) {
;     ...
;         for (int t = 0; t < nt; t += 2) {
;             const bool last = (t == nt - 2);
;             const char* a1 = cA + (size_t)(t + 1) * kstep;
;             const char* a2 = last ? nA : cA + (size_t)(t + 2) * kstep; const char* b2 = last ? nB : cB + (size_t)(t + 2) * kstep;
;             const char* a3 = a2 + kstep; const char* b3 = b2 + kstep;
;             if constexpr (SP2) {
;             PG8_LDB(B0, 0, 0); PG8_LDB(B1, 0, 1); PG8_SCHED; PG8_LDA(At, 0, 0); PG8_STAGE(PG8_SA(1, 1), a1 + hstep, voffA);
;             PG8_WAIT_V(8); PG8_WAIT_L(0); PG8_BAR; PG8_MMA(0, 0, At, B0); PG8_MMA(0, 1, At, B1); PG8_BAR; PG8_SCHED;
;             PG8_LDA(At, 0, 1); PG8_STAGE(PG8_SB(0, 0), b2, voffB); PG8_STAGE(PG8_SB(0, 1), b2 + hstep, voffB); PG8_STAGE(PG8_SA(0, 0), a2, voffA);
;             PG8_WAIT_V(8); PG8_WAIT_L(0); PG8_BAR; PG8_MMA(1, 0, At, B0); PG8_MMA(1, 1, At, B1); PG8_BAR; PG8_SCHED;
.LBB0_625:
	ds_read_b128 v[128:131], v167
	ds_read_b128 v[132:135], v167 offset:1024
	ds_read_b128 v[136:139], v167 offset:2048
	ds_read_b128 v[140:143], v167 offset:3072
	ds_read_b128 v[156:159], v168
	ds_read_b128 v[160:163], v168 offset:1024
	ds_read_b128 v[170:173], v168 offset:2048
	ds_read_b128 v[174:177], v168 offset:3072
	s_add_u32 s22, s20, 0xfffc0080
	s_addc_u32 s23, s21, -1
	s_cmp_eq_u32 s39, 12
	s_cselect_b32 s25, s15, s23
	s_cselect_b32 s24, s14, s22
	s_cselect_b32 s23, s17, s13
	s_cselect_b32 s22, s16, s11
	v_lshl_add_u64 v[210:211], s[20:21], 0, v[152:153]
	s_add_i32 m0, s19, 0xc000
	ds_read_b128 v[178:181], v169
	ds_read_b128 v[182:185], v169 offset:1024
	ds_read_b128 v[186:189], v169 offset:2048
	ds_read_b128 v[190:193], v169 offset:3072
	ds_read_b128 v[194:197], v169 offset:4096
	ds_read_b128 v[198:201], v169 offset:5120
	ds_read_b128 v[202:205], v169 offset:6144
	ds_read_b128 v[206:209], v169 offset:7168
	global_load_lds_dwordx4 v[210:211], off
	v_lshl_add_u64 v[210:211], s[20:21], 0, v[154:155]
	s_add_i32 m0, s19, 0xe000
	s_nop 0
	global_load_lds_dwordx4 v[210:211], off
	s_waitcnt vmcnt(8)
	s_waitcnt lgkmcnt(0)
	s_barrier
	s_setprio 1
	s_waitcnt lgkmcnt(0)
	v_mfma_f32_16x16x32_bf16 v[124:127], v[128:131], v[178:181], v[124:127]
	v_mfma_f32_16x16x32_bf16 v[120:123], v[136:139], v[178:181], v[120:123]
	v_mfma_f32_16x16x32_bf16 v[116:119], v[128:131], v[186:189], v[116:119]
	v_mfma_f32_16x16x32_bf16 v[112:115], v[136:139], v[186:189], v[112:115]
	v_mfma_f32_16x16x32_bf16 v[96:99], v[128:131], v[194:197], v[96:99]
	v_mfma_f32_16x16x32_bf16 v[88:91], v[136:139], v[194:197], v[88:91]
	v_mfma_f32_16x16x32_bf16 v[80:83], v[128:131], v[202:205], v[80:83]
	v_mfma_f32_16x16x32_bf16 v[72:75], v[136:139], v[202:205], v[72:75]
	v_mfma_f32_16x16x32_bf16 v[124:127], v[132:135], v[182:185], v[124:127]
	v_mfma_f32_16x16x32_bf16 v[120:123], v[140:143], v[182:185], v[120:123]
	v_mfma_f32_16x16x32_bf16 v[116:119], v[132:135], v[190:193], v[116:119]
	v_mfma_f32_16x16x32_bf16 v[112:115], v[140:143], v[190:193], v[112:115]
	v_mfma_f32_16x16x32_bf16 v[96:99], v[132:135], v[198:201], v[96:99]
	v_mfma_f32_16x16x32_bf16 v[88:91], v[140:143], v[198:201], v[88:91]
	v_mfma_f32_16x16x32_bf16 v[80:83], v[132:135], v[206:209], v[80:83]
	v_mfma_f32_16x16x32_bf16 v[72:75], v[140:143], v[206:209], v[72:75]
	s_setprio 0
	s_setprio 1
	v_mfma_f32_16x16x32_bf16 v[108:111], v[156:159], v[178:181], v[108:111]
	v_mfma_f32_16x16x32_bf16 v[104:107], v[170:173], v[178:181], v[104:107]
	v_mfma_f32_16x16x32_bf16 v[100:103], v[156:159], v[186:189], v[100:103]
	v_mfma_f32_16x16x32_bf16 v[92:95], v[170:173], v[186:189], v[92:95]
	v_mfma_f32_16x16x32_bf16 v[84:87], v[156:159], v[194:197], v[84:87]
	v_mfma_f32_16x16x32_bf16 v[76:79], v[170:173], v[194:197], v[76:79]
	v_mfma_f32_16x16x32_bf16 v[68:71], v[156:159], v[202:205], v[68:71]
	v_mfma_f32_16x16x32_bf16 v[64:67], v[170:173], v[202:205], v[64:67]
	v_mfma_f32_16x16x32_bf16 v[108:111], v[160:163], v[182:185], v[108:111]
	v_mfma_f32_16x16x32_bf16 v[104:107], v[174:177], v[182:185], v[104:107]
	v_mfma_f32_16x16x32_bf16 v[100:103], v[160:163], v[190:193], v[100:103]
	v_mfma_f32_16x16x32_bf16 v[92:95], v[174:177], v[190:193], v[92:95]
	v_mfma_f32_16x16x32_bf16 v[84:87], v[160:163], v[198:201], v[84:87]
	v_mfma_f32_16x16x32_bf16 v[76:79], v[174:177], v[198:201], v[76:79]
	v_mfma_f32_16x16x32_bf16 v[68:71], v[160:163], v[206:209], v[68:71]
	v_mfma_f32_16x16x32_bf16 v[64:67], v[174:177], v[206:209], v[64:67]
	s_setprio 0
	s_barrier
	s_add_i32 s40, s36, s26
	v_lshl_add_u64 v[210:211], s[22:23], 0, v[146:147]
	s_mov_b32 m0, s40
	ds_read_b128 v[178:181], v169 offset:16384
	ds_read_b128 v[182:185], v169 offset:17408
	ds_read_b128 v[186:189], v169 offset:18432
	ds_read_b128 v[190:193], v169 offset:19456
	ds_read_b128 v[194:197], v169 offset:20480
	ds_read_b128 v[198:201], v169 offset:21504
	ds_read_b128 v[202:205], v169 offset:22528
	ds_read_b128 v[206:209], v169 offset:23552
	global_load_lds_dwordx4 v[210:211], off
	s_add_i32 m0, s40, 0x2000
	s_add_u32 s40, s22, 0x40000
	v_lshl_add_u64 v[212:213], s[22:23], 0, v[150:151]
	s_addc_u32 s41, s23, 0
	s_add_i32 s42, s37, s26
	global_load_lds_dwordx4 v[212:213], off
	v_lshl_add_u64 v[214:215], s[40:41], 0, v[146:147]
	s_mov_b32 m0, s42
	v_lshl_add_u64 v[216:217], s[24:25], 0, v[148:149]
	global_load_lds_dwordx4 v[214:215], off
	v_lshl_add_u64 v[214:215], s[40:41], 0, v[150:151]
	s_add_i32 m0, s42, 0x2000
	s_nop 0
	global_load_lds_dwordx4 v[214:215], off
	v_lshl_add_u64 v[214:215], s[24:25], 0, v[144:145]
	s_mov_b32 m0, s19
	s_nop 0
	global_load_lds_dwordx4 v[214:215], off
	s_mov_b32 m0, s27
	s_nop 0
	global_load_lds_dwordx4 v[216:217], off
	s_waitcnt vmcnt(8)
	s_waitcnt lgkmcnt(0)
	s_barrier
; #define PG8_STAGE(bufoff, gbase, voff) do { _Pragma("unroll") for (int _i = 0; _i < 2; ++_i) \
;         __builtin_amdgcn_global_load_lds((const unsigned*)((const char*)(gbase) + (voff)[_i]), (LAS unsigned*)(lds + (bufoff) + ldsw + _i * 8192), 16, 0, 0); } while (0)
; #define PG8_LDA(dst, b, h) do { _Pragma("unroll") for (int m = 0; m < 4; ++m) _Pragma("unroll") for (int k = 0; k < 2; ++k) dst[m][k] = *(const LAS bf16x8*)(lds + PG8_SA(b, h) + aoff + m * 2048 + k * 1024); } while (0)
; #define PG8_LDB(dst, b, h) do { _Pragma("unroll") for (int n = 0; n < 2; ++n) _Pragma("unroll") for (int k = 0; k < 2; ++k) dst[n][k] = *(const LAS bf16x8*)(lds + PG8_SB(b, h) + boff + n * 2048 + k * 1024); } while (0)
; #define PG8_MMA(ai, bj, At, Bt) do { __builtin_amdgcn_s_setprio(1); _Pragma("unroll") for (int m = 0; m < 4; ++m) _Pragma("unroll") for (int n = 0; n < 2; ++n) _Pragma("unroll") for (int k = 0; k < 2; ++k) \
;         acc[ai][bj][m][n] = __builtin_amdgcn_mfma_f32_16x16x32_bf16(Bt[n][k], At[m][k], acc[ai][bj][m][n], 0, 0, 0); __builtin_amdgcn_s_setprio(0); } while (0)
; #define PG8_WAIT_V(n) asm volatile("s_waitcnt vmcnt(" #n ")" ::: "memory")
; #define PG8_WAIT_L(n) asm volatile("s_waitcnt lgkmcnt(" #n ")" ::: "memory")
; #define PG8_BAR __builtin_amdgcn_s_barrier()
; #define PG8_SCHED __builtin_amdgcn_sched_barrier(0)
; template <class Epi, bool ALIGN_EPI, bool SP2>
; __device__ __forceinline__ void gemm_phase(LAS unsigned char* lds, const Sched2& S, const Epi& E) {
;     ...
;             PG8_WAIT_V(8); PG8_WAIT_L(0); PG8_BAR; PG8_MMA(0, 0, At, B0); PG8_MMA(0, 1, At, B1); PG8_BAR; PG8_SCHED;
;             PG8_LDA(At, 0, 1); PG8_STAGE(PG8_SB(0, 0), b2, voffB); PG8_STAGE(PG8_SB(0, 1), b2 + hstep, voffB); PG8_STAGE(PG8_SA(0, 0), a2, voffA);
;             PG8_WAIT_V(8); PG8_WAIT_L(0); PG8_BAR; PG8_MMA(1, 0, At, B0); PG8_MMA(1, 1, At, B1); PG8_BAR; PG8_SCHED;
;             PG8_LDB(B0, 1, 0); PG8_LDB(B1, 1, 1); PG8_SCHED; PG8_LDA(At, 1, 0); PG8_STAGE(PG8_SA(0, 1), a2 + hstep, voffA);
;             PG8_WAIT_V(8); PG8_WAIT_L(0); PG8_BAR; PG8_MMA(0, 0, At, B0); PG8_MMA(0, 1, At, B1); PG8_BAR; PG8_SCHED;
	s_setprio 1
	s_waitcnt lgkmcnt(0)
	v_mfma_f32_16x16x32_bf16 v[60:63], v[128:131], v[178:181], v[60:63]
	v_mfma_f32_16x16x32_bf16 v[56:59], v[136:139], v[178:181], v[56:59]
	v_mfma_f32_16x16x32_bf16 v[48:51], v[128:131], v[186:189], v[48:51]
	v_mfma_f32_16x16x32_bf16 v[40:43], v[136:139], v[186:189], v[40:43]
	v_mfma_f32_16x16x32_bf16 v[32:35], v[128:131], v[194:197], v[32:35]
	v_mfma_f32_16x16x32_bf16 v[24:27], v[136:139], v[194:197], v[24:27]
	v_mfma_f32_16x16x32_bf16 v[16:19], v[128:131], v[202:205], v[16:19]
	v_mfma_f32_16x16x32_bf16 v[8:11], v[136:139], v[202:205], v[8:11]
	v_mfma_f32_16x16x32_bf16 v[60:63], v[132:135], v[182:185], v[60:63]
	v_mfma_f32_16x16x32_bf16 v[56:59], v[140:143], v[182:185], v[56:59]
	v_mfma_f32_16x16x32_bf16 v[48:51], v[132:135], v[190:193], v[48:51]
	v_mfma_f32_16x16x32_bf16 v[40:43], v[140:143], v[190:193], v[40:43]
	v_mfma_f32_16x16x32_bf16 v[32:35], v[132:135], v[198:201], v[32:35]
	v_mfma_f32_16x16x32_bf16 v[24:27], v[140:143], v[198:201], v[24:27]
	v_mfma_f32_16x16x32_bf16 v[16:19], v[132:135], v[206:209], v[16:19]
	v_mfma_f32_16x16x32_bf16 v[8:11], v[140:143], v[206:209], v[8:11]
	s_setprio 0
	s_setprio 1
	v_mfma_f32_16x16x32_bf16 v[52:55], v[156:159], v[178:181], v[52:55]
	v_mfma_f32_16x16x32_bf16 v[44:47], v[170:173], v[178:181], v[44:47]
	v_mfma_f32_16x16x32_bf16 v[36:39], v[156:159], v[186:189], v[36:39]
	v_mfma_f32_16x16x32_bf16 v[28:31], v[170:173], v[186:189], v[28:31]
	v_mfma_f32_16x16x32_bf16 v[20:23], v[156:159], v[194:197], v[20:23]
	v_mfma_f32_16x16x32_bf16 v[12:15], v[170:173], v[194:197], v[12:15]
	v_mfma_f32_16x16x32_bf16 v[4:7], v[156:159], v[202:205], v[4:7]
	v_mfma_f32_16x16x32_bf16 v[0:3], v[170:173], v[202:205], v[0:3]
	v_mfma_f32_16x16x32_bf16 v[52:55], v[160:163], v[182:185], v[52:55]
	v_mfma_f32_16x16x32_bf16 v[44:47], v[174:177], v[182:185], v[44:47]
	v_mfma_f32_16x16x32_bf16 v[36:39], v[160:163], v[190:193], v[36:39]
	v_mfma_f32_16x16x32_bf16 v[28:31], v[174:177], v[190:193], v[28:31]
	v_mfma_f32_16x16x32_bf16 v[20:23], v[160:163], v[198:201], v[20:23]
	v_mfma_f32_16x16x32_bf16 v[12:15], v[174:177], v[198:201], v[12:15]
	v_mfma_f32_16x16x32_bf16 v[4:7], v[160:163], v[206:209], v[4:7]
	v_mfma_f32_16x16x32_bf16 v[0:3], v[174:177], v[206:209], v[0:3]
	s_setprio 0
	s_barrier
	s_add_i32 s40, 0, 0x18000
	s_add_i32 s41, 0, 0x1c000
	v_add_u32_e32 v140, s40, v165
	v_add_u32_e32 v174, s41, v165
	ds_read_b128 v[128:131], v140
	ds_read_b128 v[132:135], v140 offset:1024
	ds_read_b128 v[136:139], v140 offset:2048
	ds_read_b128 v[140:143], v140 offset:3072
	ds_read_b128 v[156:159], v174
	ds_read_b128 v[160:163], v174 offset:1024
	ds_read_b128 v[170:173], v174 offset:2048
	ds_read_b128 v[174:177], v174 offset:3072
	s_add_u32 s24, s24, 0x40000
	s_addc_u32 s25, s25, 0
	s_mov_b32 m0, s28
	v_lshl_add_u64 v[218:219], s[24:25], 0, v[144:145]
	ds_read_b128 v[178:181], v169 offset:32768
	ds_read_b128 v[182:185], v169 offset:33792
	ds_read_b128 v[186:189], v169 offset:34816
	ds_read_b128 v[190:193], v169 offset:35840
	ds_read_b128 v[194:197], v169 offset:36864
	ds_read_b128 v[198:201], v169 offset:37888
	ds_read_b128 v[202:205], v169 offset:38912
	ds_read_b128 v[206:209], v169 offset:39936
	global_load_lds_dwordx4 v[218:219], off
	v_lshl_add_u64 v[218:219], s[24:25], 0, v[148:149]
	s_mov_b32 m0, s29
	s_nop 0
	global_load_lds_dwordx4 v[218:219], off
	s_waitcnt vmcnt(8)
	s_waitcnt lgkmcnt(0)
	s_barrier
	s_setprio 1
	s_waitcnt lgkmcnt(0)
	v_mfma_f32_16x16x32_bf16 v[124:127], v[128:131], v[178:181], v[124:127]
	v_mfma_f32_16x16x32_bf16 v[120:123], v[136:139], v[178:181], v[120:123]
	v_mfma_f32_16x16x32_bf16 v[116:119], v[128:131], v[186:189], v[116:119]
	v_mfma_f32_16x16x32_bf16 v[112:115], v[136:139], v[186:189], v[112:115]
	v_mfma_f32_16x16x32_bf16 v[96:99], v[128:131], v[194:197], v[96:99]
	v_mfma_f32_16x16x32_bf16 v[88:91], v[136:139], v[194:197], v[88:91]
	v_mfma_f32_16x16x32_bf16 v[80:83], v[128:131], v[202:205], v[80:83]
	v_mfma_f32_16x16x32_bf16 v[72:75], v[136:139], v[202:205], v[72:75]
	v_mfma_f32_16x16x32_bf16 v[124:127], v[132:135], v[182:185], v[124:127]
	v_mfma_f32_16x16x32_bf16 v[120:123], v[140:143], v[182:185], v[120:123]
	v_mfma_f32_16x16x32_bf16 v[116:119], v[132:135], v[190:193], v[116:119]
	v_mfma_f32_16x16x32_bf16 v[112:115], v[140:143], v[190:193], v[112:115]
	v_mfma_f32_16x16x32_bf16 v[96:99], v[132:135], v[198:201], v[96:99]
	v_mfma_f32_16x16x32_bf16 v[88:91], v[140:143], v[198:201], v[88:91]
	v_mfma_f32_16x16x32_bf16 v[80:83], v[132:135], v[206:209], v[80:83]
	v_mfma_f32_16x16x32_bf16 v[72:75], v[140:143], v[206:209], v[72:75]
	s_setprio 0
	s_setprio 1
	v_mfma_f32_16x16x32_bf16 v[108:111], v[156:159], v[178:181], v[108:111]
	v_mfma_f32_16x16x32_bf16 v[104:107], v[170:173], v[178:181], v[104:107]
	v_mfma_f32_16x16x32_bf16 v[100:103], v[156:159], v[186:189], v[100:103]
	v_mfma_f32_16x16x32_bf16 v[92:95], v[170:173], v[186:189], v[92:95]
	v_mfma_f32_16x16x32_bf16 v[84:87], v[156:159], v[194:197], v[84:87]
	v_mfma_f32_16x16x32_bf16 v[76:79], v[170:173], v[194:197], v[76:79]
	v_mfma_f32_16x16x32_bf16 v[68:71], v[156:159], v[202:205], v[68:71]
	v_mfma_f32_16x16x32_bf16 v[64:67], v[170:173], v[202:205], v[64:67]
	v_mfma_f32_16x16x32_bf16 v[108:111], v[160:163], v[182:185], v[108:111]
	v_mfma_f32_16x16x32_bf16 v[104:107], v[174:177], v[182:185], v[104:107]
	v_mfma_f32_16x16x32_bf16 v[100:103], v[160:163], v[190:193], v[100:103]
	v_mfma_f32_16x16x32_bf16 v[92:95], v[174:177], v[190:193], v[92:95]
	v_mfma_f32_16x16x32_bf16 v[84:87], v[160:163], v[198:201], v[84:87]
	v_mfma_f32_16x16x32_bf16 v[76:79], v[174:177], v[198:201], v[76:79]
	v_mfma_f32_16x16x32_bf16 v[68:71], v[160:163], v[206:209], v[68:71]
	v_mfma_f32_16x16x32_bf16 v[64:67], v[174:177], v[206:209], v[64:67]
	s_setprio 0
	s_barrier
; #define PG8_STAGE(bufoff, gbase, voff) do { _Pragma("unroll") for (int _i = 0; _i < 2; ++_i) \
;         __builtin_amdgcn_global_load_lds((const unsigned*)((const char*)(gbase) + (voff)[_i]), (LAS unsigned*)(lds + (bufoff) + ldsw + _i * 8192), 16, 0, 0); } while (0)
; #define PG8_LDA(dst, b, h) do { _Pragma("unroll") for (int m = 0; m < 4; ++m) _Pragma("unroll") for (int k = 0; k < 2; ++k) dst[m][k] = *(const LAS bf16x8*)(lds + PG8_SA(b, h) + aoff + m * 2048 + k * 1024); } while (0)
; #define PG8_LDB(dst, b, h) do { _Pragma("unroll") for (int n = 0; n < 2; ++n) _Pragma("unroll") for (int k = 0; k < 2; ++k) dst[n][k] = *(const LAS bf16x8*)(lds + PG8_SB(b, h) + boff + n * 2048 + k * 1024); } while (0)
; #define PG8_MMA(ai, bj, At, Bt) do { __builtin_amdgcn_s_setprio(1); _Pragma("unroll") for (int m = 0; m < 4; ++m) _Pragma("unroll") for (int n = 0; n < 2; ++n) _Pragma("unroll") for (int k = 0; k < 2; ++k) \
;         acc[ai][bj][m][n] = __builtin_amdgcn_mfma_f32_16x16x32_bf16(Bt[n][k], At[m][k], acc[ai][bj][m][n], 0, 0, 0); __builtin_amdgcn_s_setprio(0); } while (0)
; #define PG8_WAIT_V(n) asm volatile("s_waitcnt vmcnt(" #n ")" ::: "memory")
; #define PG8_WAIT_L(n) asm volatile("s_waitcnt lgkmcnt(" #n ")" ::: "memory")
; #define PG8_BAR __builtin_amdgcn_s_barrier()
; #define PG8_SCHED __builtin_amdgcn_sched_barrier(0)
; template <class Epi, bool ALIGN_EPI, bool SP2>
; __device__ __forceinline__ void gemm_phase(LAS unsigned char* lds, const Sched2& S, const Epi& E) {
;     ...
;         for (int t = 0; t < nt; t += 2) {
;     ...
;             PG8_LDB(B0, 1, 0); PG8_LDB(B1, 1, 1); PG8_SCHED; PG8_LDA(At, 1, 0); PG8_STAGE(PG8_SA(0, 1), a2 + hstep, voffA);
;             PG8_WAIT_V(8); PG8_WAIT_L(0); PG8_BAR; PG8_MMA(0, 0, At, B0); PG8_MMA(0, 1, At, B1); PG8_BAR; PG8_SCHED;
;             PG8_LDA(At, 1, 1); PG8_STAGE(PG8_SB(1, 0), b3, voffB); PG8_STAGE(PG8_SB(1, 1), b3 + hstep, voffB); PG8_STAGE(PG8_SA(1, 0), a3, voffA);
;             PG8_WAIT_V(8); PG8_WAIT_L(0); PG8_BAR; PG8_MMA(1, 0, At, B0); PG8_MMA(1, 1, At, B1); PG8_BAR; PG8_SCHED;
	s_add_i32 s24, s40, s26
	v_lshl_add_u64 v[210:211], v[210:211], 0, s[4:5]
	s_mov_b32 m0, s24
	ds_read_b128 v[178:181], v169 offset:49152
	ds_read_b128 v[182:185], v169 offset:50176
	ds_read_b128 v[186:189], v169 offset:51200
	ds_read_b128 v[190:193], v169 offset:52224
	ds_read_b128 v[194:197], v169 offset:53248
	ds_read_b128 v[198:201], v169 offset:54272
	ds_read_b128 v[202:205], v169 offset:55296
	ds_read_b128 v[206:209], v169 offset:56320
	global_load_lds_dwordx4 v[210:211], off
	s_add_i32 m0, s24, 0x2000
	s_add_u32 s22, s22, 0x40080
	v_lshl_add_u64 v[210:211], v[212:213], 0, s[4:5]
	s_addc_u32 s23, s23, 0
	s_add_i32 s24, s41, s26
	global_load_lds_dwordx4 v[210:211], off
	v_lshl_add_u64 v[210:211], s[22:23], 0, v[146:147]
	s_mov_b32 m0, s24
	s_nop 0
	global_load_lds_dwordx4 v[210:211], off
	v_lshl_add_u64 v[210:211], s[22:23], 0, v[150:151]
	s_add_i32 m0, s24, 0x2000
	s_nop 0
	global_load_lds_dwordx4 v[210:211], off
	v_lshl_add_u64 v[210:211], v[214:215], 0, s[4:5]
	s_mov_b32 m0, s34
	s_nop 0
	global_load_lds_dwordx4 v[210:211], off
	v_lshl_add_u64 v[210:211], v[216:217], 0, s[4:5]
	s_mov_b32 m0, s35
	s_nop 0
	global_load_lds_dwordx4 v[210:211], off
	s_waitcnt vmcnt(8)
	s_waitcnt lgkmcnt(0)
	s_barrier
	s_setprio 1
	s_waitcnt lgkmcnt(0)
	v_mfma_f32_16x16x32_bf16 v[60:63], v[128:131], v[178:181], v[60:63]
	v_mfma_f32_16x16x32_bf16 v[56:59], v[136:139], v[178:181], v[56:59]
	v_mfma_f32_16x16x32_bf16 v[48:51], v[128:131], v[186:189], v[48:51]
	v_mfma_f32_16x16x32_bf16 v[40:43], v[136:139], v[186:189], v[40:43]
	v_mfma_f32_16x16x32_bf16 v[32:35], v[128:131], v[194:197], v[32:35]
	v_mfma_f32_16x16x32_bf16 v[24:27], v[136:139], v[194:197], v[24:27]
	v_mfma_f32_16x16x32_bf16 v[16:19], v[128:131], v[202:205], v[16:19]
	v_mfma_f32_16x16x32_bf16 v[8:11], v[136:139], v[202:205], v[8:11]
	v_mfma_f32_16x16x32_bf16 v[60:63], v[132:135], v[182:185], v[60:63]
	v_mfma_f32_16x16x32_bf16 v[56:59], v[140:143], v[182:185], v[56:59]
	v_mfma_f32_16x16x32_bf16 v[48:51], v[132:135], v[190:193], v[48:51]
	v_mfma_f32_16x16x32_bf16 v[40:43], v[140:143], v[190:193], v[40:43]
	v_mfma_f32_16x16x32_bf16 v[32:35], v[132:135], v[198:201], v[32:35]
	v_mfma_f32_16x16x32_bf16 v[24:27], v[140:143], v[198:201], v[24:27]
	v_mfma_f32_16x16x32_bf16 v[16:19], v[132:135], v[206:209], v[16:19]
	v_mfma_f32_16x16x32_bf16 v[8:11], v[140:143], v[206:209], v[8:11]
	s_setprio 0
	s_setprio 1
	v_mfma_f32_16x16x32_bf16 v[52:55], v[156:159], v[178:181], v[52:55]
	v_mfma_f32_16x16x32_bf16 v[44:47], v[170:173], v[178:181], v[44:47]
	v_mfma_f32_16x16x32_bf16 v[36:39], v[156:159], v[186:189], v[36:39]
	v_mfma_f32_16x16x32_bf16 v[28:31], v[170:173], v[186:189], v[28:31]
	v_mfma_f32_16x16x32_bf16 v[20:23], v[156:159], v[194:197], v[20:23]
	v_mfma_f32_16x16x32_bf16 v[12:15], v[170:173], v[194:197], v[12:15]
	v_mfma_f32_16x16x32_bf16 v[4:7], v[156:159], v[202:205], v[4:7]
	v_mfma_f32_16x16x32_bf16 v[0:3], v[170:173], v[202:205], v[0:3]
	v_mfma_f32_16x16x32_bf16 v[52:55], v[160:163], v[182:185], v[52:55]
	v_mfma_f32_16x16x32_bf16 v[44:47], v[174:177], v[182:185], v[44:47]
	v_mfma_f32_16x16x32_bf16 v[36:39], v[160:163], v[190:193], v[36:39]
	v_mfma_f32_16x16x32_bf16 v[28:31], v[174:177], v[190:193], v[28:31]
	v_mfma_f32_16x16x32_bf16 v[20:23], v[160:163], v[198:201], v[20:23]
	v_mfma_f32_16x16x32_bf16 v[12:15], v[174:177], v[198:201], v[12:15]
	v_mfma_f32_16x16x32_bf16 v[4:7], v[160:163], v[206:209], v[4:7]
	v_mfma_f32_16x16x32_bf16 v[0:3], v[174:177], v[206:209], v[0:3]
	s_setprio 0
	s_add_i32 s39, s39, 2
	s_add_u32 s20, s20, 0x100
	s_addc_u32 s21, s21, 0
	s_add_u32 s11, s11, 0x100
	s_addc_u32 s13, s13, 0
	s_cmp_gt_u32 s39, 13
	s_barrier
	s_cbranch_scc0 .LBB0_625
	s_and_b64 vcc, exec, s[6:7]
	s_cbranch_vccz .LBB0_628
	s_barrier
